# attention: softmax fill VALU placed between the two MFMAs of each fragment step (in-order issue: VALU issues under the first MFMA)
# speedup vs baseline: 1.0079x; 1.0077x over previous
.Lattn_loop:
	s_waitcnt lgkmcnt(6)
	v_mfma_f32_16x16x32_bf16 v[192:195], v[166:169], v[98:101], 0
	v_add_f32_e32 v130, v66, v67
	v_add_f32_e32 v131, v68, v69
	v_mfma_f32_16x16x32_bf16 v[208:211], v[166:169], v[114:117], 0
	ds_read_b128 v[166:169], v185 offset:49152
	s_add_i32 m0, s45, 0x18000
	v_add_f32_e32 v130, v70, v130
	global_load_lds_dwordx4 v152, s[64:65]
	v_mfma_f32_16x16x32_bf16 v[196:199], v[170:173], v[98:101], 0
	v_add_f32_e32 v131, v71, v131
	v_add_f32_e32 v130, v72, v130
	v_mfma_f32_16x16x32_bf16 v[212:215], v[170:173], v[114:117], 0
	ds_read_b128 v[170:173], v185 offset:53248
	s_add_i32 m0, s45, 0x1c000
	v_add_f32_e32 v131, v73, v131
	global_load_lds_dwordx4 v150, s[62:63]
	s_waitcnt lgkmcnt(6)
	v_mfma_f32_16x16x32_bf16 v[200:203], v[174:177], v[98:101], 0
	v_add_f32_e32 v130, v74, v130
	v_add_f32_e32 v131, v75, v131
	v_mfma_f32_16x16x32_bf16 v[216:219], v[174:177], v[114:117], 0
	ds_read_b128 v[174:177], v185 offset:57344
	s_add_i32 m0, s45, 0x1a000
	v_add_f32_e32 v130, v76, v130
	global_load_lds_dwordx4 v153, s[64:65]
	v_mfma_f32_16x16x32_bf16 v[204:207], v[178:181], v[98:101], 0
	v_add_f32_e32 v131, v77, v131
	v_add_f32_e32 v130, v78, v130
	v_mfma_f32_16x16x32_bf16 v[220:223], v[178:181], v[114:117], 0
	ds_read_b128 v[178:181], v185 offset:61440
	s_add_i32 m0, s45, 0x1e000
	v_add_f32_e32 v131, v79, v131
	global_load_lds_dwordx4 v151, s[62:63]
	s_add_u32 s62, s62, 0x4000
	s_addc_u32 s63, s63, 0
	s_add_u32 s64, s64, 0x4000
	s_addc_u32 s65, s65, 0
	s_waitcnt lgkmcnt(6)
	v_mfma_f32_16x16x32_bf16 v[192:195], v[224:227], v[102:105], v[192:195]
	v_add_f32_e32 v130, v80, v130
	v_add_f32_e32 v131, v81, v131
	v_mfma_f32_16x16x32_bf16 v[208:211], v[224:227], v[118:121], v[208:211]
	ds_read_b128 v[224:227], v186 offset:49152
	v_add_f32_e32 v130, v130, v131
	v_mfma_f32_16x16x32_bf16 v[196:199], v[228:231], v[102:105], v[196:199]
	v_add_f32_e32 v165, v165, v130
	v_add_f32_e32 v132, v82, v83
	v_mfma_f32_16x16x32_bf16 v[212:215], v[228:231], v[118:121], v[212:215]
	ds_read_b128 v[228:231], v186 offset:53248
	v_add_f32_e32 v133, v84, v85
	s_waitcnt lgkmcnt(6)
	v_mfma_f32_16x16x32_bf16 v[200:203], v[232:235], v[102:105], v[200:203]
	v_add_f32_e32 v132, v86, v132
	v_add_f32_e32 v133, v87, v133
	v_mfma_f32_16x16x32_bf16 v[216:219], v[232:235], v[118:121], v[216:219]
	ds_read_b128 v[232:235], v186 offset:57344
	v_add_f32_e32 v132, v88, v132
	v_mfma_f32_16x16x32_bf16 v[204:207], v[236:239], v[102:105], v[204:207]
	v_add_f32_e32 v133, v89, v133
	v_add_f32_e32 v132, v90, v132
	v_mfma_f32_16x16x32_bf16 v[220:223], v[236:239], v[118:121], v[220:223]
	ds_read_b128 v[236:239], v186 offset:61440
	v_add_f32_e32 v133, v91, v133
	s_waitcnt lgkmcnt(6)
	v_mfma_f32_16x16x32_bf16 v[192:195], v[166:169], v[106:109], v[192:195]
	v_add_f32_e32 v132, v92, v132
	v_add_f32_e32 v133, v93, v133
	v_mfma_f32_16x16x32_bf16 v[208:211], v[166:169], v[122:125], v[208:211]
	ds_read_b64_tr_b16 v[166:167], v240 offset:0
	ds_read_b64_tr_b16 v[168:169], v240 offset:4096
	v_add_f32_e32 v132, v94, v132
	v_mfma_f32_16x16x32_bf16 v[196:199], v[170:173], v[106:109], v[196:199]
	v_add_f32_e32 v133, v95, v133
	v_add_f32_e32 v132, v96, v132
	v_mfma_f32_16x16x32_bf16 v[212:215], v[170:173], v[122:125], v[212:215]
	ds_read_b64_tr_b16 v[170:171], v241 offset:0
	ds_read_b64_tr_b16 v[172:173], v241 offset:4096
	v_add_f32_e32 v133, v97, v133
	s_waitcnt lgkmcnt(8)
	v_mfma_f32_16x16x32_bf16 v[200:203], v[174:177], v[106:109], v[200:203]
	v_add_f32_e32 v132, v132, v133
	v_add_f32_e32 v163, v163, v132
	v_mfma_f32_16x16x32_bf16 v[216:219], v[174:177], v[122:125], v[216:219]
	ds_read_b64_tr_b16 v[174:175], v242 offset:0
	ds_read_b64_tr_b16 v[176:177], v242 offset:4096
	v_cvt_pk_bf16_f32 v66, v66, v67
	v_mfma_f32_16x16x32_bf16 v[204:207], v[178:181], v[106:109], v[204:207]
	v_cvt_pk_bf16_f32 v67, v68, v69
	v_cvt_pk_bf16_f32 v68, v70, v71
	v_mfma_f32_16x16x32_bf16 v[220:223], v[178:181], v[122:125], v[220:223]
	ds_read_b64_tr_b16 v[178:179], v243 offset:0
	ds_read_b64_tr_b16 v[180:181], v243 offset:4096
	v_cvt_pk_bf16_f32 v69, v72, v73
	s_waitcnt lgkmcnt(10)
	v_mfma_f32_16x16x32_bf16 v[192:195], v[224:227], v[110:113], v[192:195]
	v_cvt_pk_bf16_f32 v74, v74, v75
	v_cvt_pk_bf16_f32 v75, v76, v77
	v_mfma_f32_16x16x32_bf16 v[208:211], v[224:227], v[126:129], v[208:211]
	ds_read_b64_tr_b16 v[224:225], v244 offset:0
	ds_read_b64_tr_b16 v[226:227], v244 offset:4096
	v_cvt_pk_bf16_f32 v76, v78, v79
	v_mfma_f32_16x16x32_bf16 v[196:199], v[228:231], v[110:113], v[196:199]
	v_cvt_pk_bf16_f32 v77, v80, v81
	v_cvt_pk_bf16_f32 v82, v82, v83
	v_mfma_f32_16x16x32_bf16 v[212:215], v[228:231], v[126:129], v[212:215]
	v_cvt_pk_bf16_f32 v83, v84, v85
	s_waitcnt lgkmcnt(10)
	v_mfma_f32_16x16x32_bf16 v[200:203], v[232:235], v[110:113], v[200:203]
	v_cvt_pk_bf16_f32 v84, v86, v87
	v_cvt_pk_bf16_f32 v85, v88, v89
	v_mfma_f32_16x16x32_bf16 v[216:219], v[232:235], v[126:129], v[216:219]
	v_cvt_pk_bf16_f32 v90, v90, v91
	v_mfma_f32_16x16x32_bf16 v[204:207], v[236:239], v[110:113], v[204:207]
	v_cvt_pk_bf16_f32 v91, v92, v93
	v_cvt_pk_bf16_f32 v92, v94, v95
	v_mfma_f32_16x16x32_bf16 v[220:223], v[236:239], v[126:129], v[220:223]
	v_cvt_pk_bf16_f32 v93, v96, v97
	s_waitcnt lgkmcnt(6)
	v_mfma_f32_16x16x32_bf16 v[2:5], v[66:69], v[166:169], v[2:5]
	v_mfma_f32_16x16x32_bf16 v[34:37], v[82:85], v[166:169], v[34:37]
	ds_read_b64_tr_b16 v[228:229], v245 offset:0
	ds_read_b64_tr_b16 v[230:231], v245 offset:4096
	v_mfma_f32_16x16x32_bf16 v[6:9], v[66:69], v[170:173], v[6:9]
	v_mfma_f32_16x16x32_bf16 v[38:41], v[82:85], v[170:173], v[38:41]
	ds_read_b64_tr_b16 v[232:233], v246 offset:0
	ds_read_b64_tr_b16 v[234:235], v246 offset:4096
	s_waitcnt lgkmcnt(6)
	v_mfma_f32_16x16x32_bf16 v[10:13], v[66:69], v[174:177], v[10:13]
	v_exp_f32_e32 v192, v192
	v_exp_f32_e32 v193, v193
	v_mfma_f32_16x16x32_bf16 v[42:45], v[82:85], v[174:177], v[42:45]
	ds_read_b64_tr_b16 v[236:237], v247 offset:0
	ds_read_b64_tr_b16 v[238:239], v247 offset:4096
	v_exp_f32_e32 v194, v194
	v_mfma_f32_16x16x32_bf16 v[14:17], v[66:69], v[178:181], v[14:17]
	v_exp_f32_e32 v195, v195
	v_mfma_f32_16x16x32_bf16 v[46:49], v[82:85], v[178:181], v[46:49]
	ds_read_b64_tr_b16 v[166:167], v240 offset:8192
	ds_read_b64_tr_b16 v[168:169], v240 offset:12288
	v_exp_f32_e32 v208, v208
	s_waitcnt lgkmcnt(6)
	v_mfma_f32_16x16x32_bf16 v[18:21], v[66:69], v[224:227], v[18:21]
	v_exp_f32_e32 v209, v209
	v_mfma_f32_16x16x32_bf16 v[50:53], v[82:85], v[224:227], v[50:53]
	ds_read_b64_tr_b16 v[170:171], v241 offset:8192
	ds_read_b64_tr_b16 v[172:173], v241 offset:12288
	v_exp_f32_e32 v210, v210
	v_mfma_f32_16x16x32_bf16 v[22:25], v[66:69], v[228:231], v[22:25]
	v_exp_f32_e32 v211, v211
	v_exp_f32_e32 v196, v196
	v_mfma_f32_16x16x32_bf16 v[54:57], v[82:85], v[228:231], v[54:57]
	ds_read_b64_tr_b16 v[174:175], v242 offset:8192
	ds_read_b64_tr_b16 v[176:177], v242 offset:12288
	v_exp_f32_e32 v197, v197
	s_waitcnt lgkmcnt(6)
	v_mfma_f32_16x16x32_bf16 v[26:29], v[66:69], v[232:235], v[26:29]
	v_exp_f32_e32 v198, v198
	v_mfma_f32_16x16x32_bf16 v[58:61], v[82:85], v[232:235], v[58:61]
	ds_read_b64_tr_b16 v[178:179], v243 offset:8192
	ds_read_b64_tr_b16 v[180:181], v243 offset:12288
	v_exp_f32_e32 v199, v199
	v_mfma_f32_16x16x32_bf16 v[30:33], v[66:69], v[236:239], v[30:33]
	v_exp_f32_e32 v212, v212
	v_mfma_f32_16x16x32_bf16 v[62:65], v[82:85], v[236:239], v[62:65]
	ds_read_b64_tr_b16 v[224:225], v244 offset:8192
	ds_read_b64_tr_b16 v[226:227], v244 offset:12288
	v_exp_f32_e32 v213, v213
	s_waitcnt lgkmcnt(6)
	v_mfma_f32_16x16x32_bf16 v[2:5], v[74:77], v[166:169], v[2:5]
	v_exp_f32_e32 v214, v214
	v_mfma_f32_16x16x32_bf16 v[34:37], v[90:93], v[166:169], v[34:37]
	ds_read_b64_tr_b16 v[228:229], v245 offset:8192
	ds_read_b64_tr_b16 v[230:231], v245 offset:12288
	ds_read_b128 v[166:169], v187 offset:16384
	v_exp_f32_e32 v215, v215
	v_mfma_f32_16x16x32_bf16 v[6:9], v[74:77], v[170:173], v[6:9]
	v_exp_f32_e32 v200, v200
	v_exp_f32_e32 v201, v201
	v_mfma_f32_16x16x32_bf16 v[38:41], v[90:93], v[170:173], v[38:41]
	ds_read_b64_tr_b16 v[232:233], v246 offset:8192
	ds_read_b64_tr_b16 v[234:235], v246 offset:12288
	ds_read_b128 v[170:173], v187 offset:20480
	v_exp_f32_e32 v202, v202
	s_waitcnt lgkmcnt(8)
	v_mfma_f32_16x16x32_bf16 v[10:13], v[74:77], v[174:177], v[10:13]
	v_exp_f32_e32 v203, v203
	v_mfma_f32_16x16x32_bf16 v[42:45], v[90:93], v[174:177], v[42:45]
	ds_read_b64_tr_b16 v[236:237], v247 offset:8192
	ds_read_b64_tr_b16 v[238:239], v247 offset:12288
	ds_read_b128 v[174:177], v187 offset:24576
	v_exp_f32_e32 v216, v216
	v_mfma_f32_16x16x32_bf16 v[14:17], v[74:77], v[178:181], v[14:17]
	v_exp_f32_e32 v217, v217
	v_mfma_f32_16x16x32_bf16 v[46:49], v[90:93], v[178:181], v[46:49]
	ds_read_b128 v[178:181], v187 offset:28672
	v_exp_f32_e32 v218, v218
	s_waitcnt lgkmcnt(8)
	v_mfma_f32_16x16x32_bf16 v[18:21], v[74:77], v[224:227], v[18:21]
	v_exp_f32_e32 v219, v219
	v_exp_f32_e32 v204, v204
	v_mfma_f32_16x16x32_bf16 v[50:53], v[90:93], v[224:227], v[50:53]
	ds_read_b128 v[224:227], v188 offset:16384
	v_exp_f32_e32 v205, v205
	v_mfma_f32_16x16x32_bf16 v[22:25], v[74:77], v[228:231], v[22:25]
	v_exp_f32_e32 v206, v206
	v_mfma_f32_16x16x32_bf16 v[54:57], v[90:93], v[228:231], v[54:57]
	ds_read_b128 v[228:231], v188 offset:20480
	v_exp_f32_e32 v207, v207
	s_waitcnt lgkmcnt(4)
	v_mfma_f32_16x16x32_bf16 v[26:29], v[74:77], v[232:235], v[26:29]
	v_exp_f32_e32 v220, v220
	v_mfma_f32_16x16x32_bf16 v[58:61], v[90:93], v[232:235], v[58:61]
	ds_read_b128 v[232:235], v188 offset:24576
	v_exp_f32_e32 v221, v221
	v_mfma_f32_16x16x32_bf16 v[30:33], v[74:77], v[236:239], v[30:33]
	v_exp_f32_e32 v222, v222
	v_mfma_f32_16x16x32_bf16 v[62:65], v[90:93], v[236:239], v[62:65]
	ds_read_b128 v[236:239], v188 offset:28672
	v_exp_f32_e32 v223, v223
	s_waitcnt vmcnt(0)
	s_barrier
	v_mfma_f32_16x16x32_bf16 v[66:69], v[166:169], v[98:101], 0
	v_add_f32_e32 v130, v192, v193
	v_add_f32_e32 v131, v194, v195
	v_mfma_f32_16x16x32_bf16 v[82:85], v[166:169], v[114:117], 0
	ds_read_b128 v[166:169], v189 offset:16384
	s_add_i32 m0, s45, 0x0
	v_add_f32_e32 v130, v196, v130
	global_load_lds_dwordx4 v152, s[64:65]
	v_mfma_f32_16x16x32_bf16 v[70:73], v[170:173], v[98:101], 0
	v_add_f32_e32 v131, v197, v131
	v_add_f32_e32 v130, v198, v130
	v_mfma_f32_16x16x32_bf16 v[86:89], v[170:173], v[114:117], 0
	ds_read_b128 v[170:173], v189 offset:20480
	s_add_i32 m0, s45, 0x4000
	v_add_f32_e32 v131, v199, v131
	global_load_lds_dwordx4 v150, s[62:63]
	s_waitcnt lgkmcnt(6)
	v_mfma_f32_16x16x32_bf16 v[74:77], v[174:177], v[98:101], 0
	v_add_f32_e32 v130, v200, v130
	v_add_f32_e32 v131, v201, v131
	v_mfma_f32_16x16x32_bf16 v[90:93], v[174:177], v[114:117], 0
	ds_read_b128 v[174:177], v189 offset:24576
	s_add_i32 m0, s45, 0x2000
	v_add_f32_e32 v130, v202, v130
	global_load_lds_dwordx4 v153, s[64:65]
	v_mfma_f32_16x16x32_bf16 v[78:81], v[178:181], v[98:101], 0
	v_add_f32_e32 v131, v203, v131
	v_add_f32_e32 v130, v204, v130
	v_mfma_f32_16x16x32_bf16 v[94:97], v[178:181], v[114:117], 0
	ds_read_b128 v[178:181], v189 offset:28672
	s_add_i32 m0, s45, 0x6000
	v_add_f32_e32 v131, v205, v131
	global_load_lds_dwordx4 v151, s[62:63]
	s_add_u32 s62, s62, 0x4000
	s_addc_u32 s63, s63, 0
	s_add_u32 s64, s64, 0x4000
	s_addc_u32 s65, s65, 0
	s_waitcnt lgkmcnt(6)
	v_mfma_f32_16x16x32_bf16 v[66:69], v[224:227], v[102:105], v[66:69]
	v_add_f32_e32 v130, v206, v130
	v_add_f32_e32 v131, v207, v131
	v_mfma_f32_16x16x32_bf16 v[82:85], v[224:227], v[118:121], v[82:85]
	ds_read_b128 v[224:227], v190 offset:16384
	v_add_f32_e32 v130, v130, v131
	v_mfma_f32_16x16x32_bf16 v[70:73], v[228:231], v[102:105], v[70:73]
	v_add_f32_e32 v165, v165, v130
	v_add_f32_e32 v132, v208, v209
	v_mfma_f32_16x16x32_bf16 v[86:89], v[228:231], v[118:121], v[86:89]
	ds_read_b128 v[228:231], v190 offset:20480
	v_add_f32_e32 v133, v210, v211
	s_waitcnt lgkmcnt(6)
	v_mfma_f32_16x16x32_bf16 v[74:77], v[232:235], v[102:105], v[74:77]
	v_add_f32_e32 v132, v212, v132
	v_add_f32_e32 v133, v213, v133
	v_mfma_f32_16x16x32_bf16 v[90:93], v[232:235], v[118:121], v[90:93]
	ds_read_b128 v[232:235], v190 offset:24576
	v_add_f32_e32 v132, v214, v132
	v_mfma_f32_16x16x32_bf16 v[78:81], v[236:239], v[102:105], v[78:81]
	v_add_f32_e32 v133, v215, v133
	v_add_f32_e32 v132, v216, v132
	v_mfma_f32_16x16x32_bf16 v[94:97], v[236:239], v[118:121], v[94:97]
	ds_read_b128 v[236:239], v190 offset:28672
	v_add_f32_e32 v133, v217, v133
	s_waitcnt lgkmcnt(6)
	v_mfma_f32_16x16x32_bf16 v[66:69], v[166:169], v[106:109], v[66:69]
	v_add_f32_e32 v132, v218, v132
	v_add_f32_e32 v133, v219, v133
	v_mfma_f32_16x16x32_bf16 v[82:85], v[166:169], v[122:125], v[82:85]
	ds_read_b64_tr_b16 v[166:167], v240 offset:32768
	ds_read_b64_tr_b16 v[168:169], v240 offset:36864
	v_add_f32_e32 v132, v220, v132
	v_mfma_f32_16x16x32_bf16 v[70:73], v[170:173], v[106:109], v[70:73]
	v_add_f32_e32 v133, v221, v133
	v_add_f32_e32 v132, v222, v132
	v_mfma_f32_16x16x32_bf16 v[86:89], v[170:173], v[122:125], v[86:89]
	ds_read_b64_tr_b16 v[170:171], v241 offset:32768
	ds_read_b64_tr_b16 v[172:173], v241 offset:36864
	v_add_f32_e32 v133, v223, v133
	s_waitcnt lgkmcnt(8)
	v_mfma_f32_16x16x32_bf16 v[74:77], v[174:177], v[106:109], v[74:77]
	v_add_f32_e32 v132, v132, v133
	v_add_f32_e32 v163, v163, v132
	v_mfma_f32_16x16x32_bf16 v[90:93], v[174:177], v[122:125], v[90:93]
	ds_read_b64_tr_b16 v[174:175], v242 offset:32768
	ds_read_b64_tr_b16 v[176:177], v242 offset:36864
	v_cvt_pk_bf16_f32 v192, v192, v193
	v_mfma_f32_16x16x32_bf16 v[78:81], v[178:181], v[106:109], v[78:81]
	v_cvt_pk_bf16_f32 v193, v194, v195
	v_cvt_pk_bf16_f32 v194, v196, v197
	v_mfma_f32_16x16x32_bf16 v[94:97], v[178:181], v[122:125], v[94:97]
	ds_read_b64_tr_b16 v[178:179], v243 offset:32768
	ds_read_b64_tr_b16 v[180:181], v243 offset:36864
	v_cvt_pk_bf16_f32 v195, v198, v199
	s_waitcnt lgkmcnt(10)
	v_mfma_f32_16x16x32_bf16 v[66:69], v[224:227], v[110:113], v[66:69]
	v_cvt_pk_bf16_f32 v200, v200, v201
	v_cvt_pk_bf16_f32 v201, v202, v203
	v_mfma_f32_16x16x32_bf16 v[82:85], v[224:227], v[126:129], v[82:85]
	ds_read_b64_tr_b16 v[224:225], v244 offset:32768
	ds_read_b64_tr_b16 v[226:227], v244 offset:36864
	v_cvt_pk_bf16_f32 v202, v204, v205
	v_mfma_f32_16x16x32_bf16 v[70:73], v[228:231], v[110:113], v[70:73]
	v_cvt_pk_bf16_f32 v203, v206, v207
	v_cvt_pk_bf16_f32 v208, v208, v209
	v_mfma_f32_16x16x32_bf16 v[86:89], v[228:231], v[126:129], v[86:89]
	v_cvt_pk_bf16_f32 v209, v210, v211
	s_waitcnt lgkmcnt(10)
	v_mfma_f32_16x16x32_bf16 v[74:77], v[232:235], v[110:113], v[74:77]
	v_cvt_pk_bf16_f32 v210, v212, v213
	v_cvt_pk_bf16_f32 v211, v214, v215
	v_mfma_f32_16x16x32_bf16 v[90:93], v[232:235], v[126:129], v[90:93]
	v_cvt_pk_bf16_f32 v216, v216, v217
	v_mfma_f32_16x16x32_bf16 v[78:81], v[236:239], v[110:113], v[78:81]
	v_cvt_pk_bf16_f32 v217, v218, v219
	v_cvt_pk_bf16_f32 v218, v220, v221
	v_mfma_f32_16x16x32_bf16 v[94:97], v[236:239], v[126:129], v[94:97]
	v_cvt_pk_bf16_f32 v219, v222, v223
	s_waitcnt lgkmcnt(6)
	v_mfma_f32_16x16x32_bf16 v[2:5], v[192:195], v[166:169], v[2:5]
	v_mfma_f32_16x16x32_bf16 v[34:37], v[208:211], v[166:169], v[34:37]
	ds_read_b64_tr_b16 v[228:229], v245 offset:32768
	ds_read_b64_tr_b16 v[230:231], v245 offset:36864
	v_mfma_f32_16x16x32_bf16 v[6:9], v[192:195], v[170:173], v[6:9]
	v_mfma_f32_16x16x32_bf16 v[38:41], v[208:211], v[170:173], v[38:41]
	ds_read_b64_tr_b16 v[232:233], v246 offset:32768
	ds_read_b64_tr_b16 v[234:235], v246 offset:36864
	s_waitcnt lgkmcnt(6)
	v_mfma_f32_16x16x32_bf16 v[10:13], v[192:195], v[174:177], v[10:13]
	v_exp_f32_e32 v66, v66
	v_exp_f32_e32 v67, v67
	v_mfma_f32_16x16x32_bf16 v[42:45], v[208:211], v[174:177], v[42:45]
	ds_read_b64_tr_b16 v[236:237], v247 offset:32768
	ds_read_b64_tr_b16 v[238:239], v247 offset:36864
	v_exp_f32_e32 v68, v68
	v_mfma_f32_16x16x32_bf16 v[14:17], v[192:195], v[178:181], v[14:17]
	v_exp_f32_e32 v69, v69
	v_mfma_f32_16x16x32_bf16 v[46:49], v[208:211], v[178:181], v[46:49]
	ds_read_b64_tr_b16 v[166:167], v240 offset:40960
	ds_read_b64_tr_b16 v[168:169], v240 offset:45056
	v_exp_f32_e32 v82, v82
	s_waitcnt lgkmcnt(6)
	v_mfma_f32_16x16x32_bf16 v[18:21], v[192:195], v[224:227], v[18:21]
	v_exp_f32_e32 v83, v83
	v_mfma_f32_16x16x32_bf16 v[50:53], v[208:211], v[224:227], v[50:53]
	ds_read_b64_tr_b16 v[170:171], v241 offset:40960
	ds_read_b64_tr_b16 v[172:173], v241 offset:45056
	v_exp_f32_e32 v84, v84
	v_mfma_f32_16x16x32_bf16 v[22:25], v[192:195], v[228:231], v[22:25]
	v_exp_f32_e32 v85, v85
	v_exp_f32_e32 v70, v70
	v_mfma_f32_16x16x32_bf16 v[54:57], v[208:211], v[228:231], v[54:57]
	ds_read_b64_tr_b16 v[174:175], v242 offset:40960
	ds_read_b64_tr_b16 v[176:177], v242 offset:45056
	v_exp_f32_e32 v71, v71
	s_waitcnt lgkmcnt(6)
	v_mfma_f32_16x16x32_bf16 v[26:29], v[192:195], v[232:235], v[26:29]
	v_exp_f32_e32 v72, v72
	v_mfma_f32_16x16x32_bf16 v[58:61], v[208:211], v[232:235], v[58:61]
	ds_read_b64_tr_b16 v[178:179], v243 offset:40960
	ds_read_b64_tr_b16 v[180:181], v243 offset:45056
	v_exp_f32_e32 v73, v73
	v_mfma_f32_16x16x32_bf16 v[30:33], v[192:195], v[236:239], v[30:33]
	v_exp_f32_e32 v86, v86
	v_mfma_f32_16x16x32_bf16 v[62:65], v[208:211], v[236:239], v[62:65]
	ds_read_b64_tr_b16 v[224:225], v244 offset:40960
	ds_read_b64_tr_b16 v[226:227], v244 offset:45056
	v_exp_f32_e32 v87, v87
	s_waitcnt lgkmcnt(6)
	v_mfma_f32_16x16x32_bf16 v[2:5], v[200:203], v[166:169], v[2:5]
	v_exp_f32_e32 v88, v88
	v_mfma_f32_16x16x32_bf16 v[34:37], v[216:219], v[166:169], v[34:37]
	ds_read_b64_tr_b16 v[228:229], v245 offset:40960
	ds_read_b64_tr_b16 v[230:231], v245 offset:45056
	ds_read_b128 v[166:169], v187 offset:49152
	v_exp_f32_e32 v89, v89
	v_mfma_f32_16x16x32_bf16 v[6:9], v[200:203], v[170:173], v[6:9]
	v_exp_f32_e32 v74, v74
	v_exp_f32_e32 v75, v75
	v_mfma_f32_16x16x32_bf16 v[38:41], v[216:219], v[170:173], v[38:41]
	ds_read_b64_tr_b16 v[232:233], v246 offset:40960
	ds_read_b64_tr_b16 v[234:235], v246 offset:45056
	ds_read_b128 v[170:173], v187 offset:53248
	v_exp_f32_e32 v76, v76
	s_waitcnt lgkmcnt(8)
	v_mfma_f32_16x16x32_bf16 v[10:13], v[200:203], v[174:177], v[10:13]
	v_exp_f32_e32 v77, v77
	v_mfma_f32_16x16x32_bf16 v[42:45], v[216:219], v[174:177], v[42:45]
	ds_read_b64_tr_b16 v[236:237], v247 offset:40960
	ds_read_b64_tr_b16 v[238:239], v247 offset:45056
	ds_read_b128 v[174:177], v187 offset:57344
	v_exp_f32_e32 v90, v90
	v_mfma_f32_16x16x32_bf16 v[14:17], v[200:203], v[178:181], v[14:17]
	v_exp_f32_e32 v91, v91
	v_mfma_f32_16x16x32_bf16 v[46:49], v[216:219], v[178:181], v[46:49]
	ds_read_b128 v[178:181], v187 offset:61440
	v_exp_f32_e32 v92, v92
	s_waitcnt lgkmcnt(8)
	v_mfma_f32_16x16x32_bf16 v[18:21], v[200:203], v[224:227], v[18:21]
	v_exp_f32_e32 v93, v93
	v_exp_f32_e32 v78, v78
	v_mfma_f32_16x16x32_bf16 v[50:53], v[216:219], v[224:227], v[50:53]
	ds_read_b128 v[224:227], v188 offset:49152
	v_exp_f32_e32 v79, v79
	v_mfma_f32_16x16x32_bf16 v[22:25], v[200:203], v[228:231], v[22:25]
	v_exp_f32_e32 v80, v80
	v_mfma_f32_16x16x32_bf16 v[54:57], v[216:219], v[228:231], v[54:57]
	ds_read_b128 v[228:231], v188 offset:53248
	v_exp_f32_e32 v81, v81
	s_waitcnt lgkmcnt(4)
	v_mfma_f32_16x16x32_bf16 v[26:29], v[200:203], v[232:235], v[26:29]
	v_exp_f32_e32 v94, v94
	v_mfma_f32_16x16x32_bf16 v[58:61], v[216:219], v[232:235], v[58:61]
	ds_read_b128 v[232:235], v188 offset:57344
	v_exp_f32_e32 v95, v95
	v_mfma_f32_16x16x32_bf16 v[30:33], v[200:203], v[236:239], v[30:33]
	v_exp_f32_e32 v96, v96
	v_mfma_f32_16x16x32_bf16 v[62:65], v[216:219], v[236:239], v[62:65]
	ds_read_b128 v[236:239], v188 offset:61440
	v_exp_f32_e32 v97, v97
	s_waitcnt vmcnt(0)
	s_barrier
	v_mfma_f32_16x16x32_bf16 v[192:195], v[166:169], v[98:101], 0
	v_add_f32_e32 v130, v66, v67
	v_add_f32_e32 v131, v68, v69
	v_mfma_f32_16x16x32_bf16 v[208:211], v[166:169], v[114:117], 0
	ds_read_b128 v[166:169], v189 offset:49152
	s_add_i32 m0, s45, 0x8000
	v_add_f32_e32 v130, v70, v130
	global_load_lds_dwordx4 v152, s[64:65]
	v_mfma_f32_16x16x32_bf16 v[196:199], v[170:173], v[98:101], 0
	v_add_f32_e32 v131, v71, v131
	v_add_f32_e32 v130, v72, v130
	v_mfma_f32_16x16x32_bf16 v[212:215], v[170:173], v[114:117], 0
	ds_read_b128 v[170:173], v189 offset:53248
	s_add_i32 m0, s45, 0xc000
	v_add_f32_e32 v131, v73, v131
	global_load_lds_dwordx4 v150, s[62:63]
	s_waitcnt lgkmcnt(6)
	v_mfma_f32_16x16x32_bf16 v[200:203], v[174:177], v[98:101], 0
	v_add_f32_e32 v130, v74, v130
	v_add_f32_e32 v131, v75, v131
	v_mfma_f32_16x16x32_bf16 v[216:219], v[174:177], v[114:117], 0
	ds_read_b128 v[174:177], v189 offset:57344
	s_add_i32 m0, s45, 0xa000
	v_add_f32_e32 v130, v76, v130
	global_load_lds_dwordx4 v153, s[64:65]
	v_mfma_f32_16x16x32_bf16 v[204:207], v[178:181], v[98:101], 0
	v_add_f32_e32 v131, v77, v131
	v_add_f32_e32 v130, v78, v130
	v_mfma_f32_16x16x32_bf16 v[220:223], v[178:181], v[114:117], 0
	ds_read_b128 v[178:181], v189 offset:61440
	s_add_i32 m0, s45, 0xe000
	v_add_f32_e32 v131, v79, v131
	global_load_lds_dwordx4 v151, s[62:63]
	s_add_u32 s62, s62, 0x4000
	s_addc_u32 s63, s63, 0
	s_add_u32 s64, s64, 0x4000
	s_addc_u32 s65, s65, 0
	s_waitcnt lgkmcnt(6)
	v_mfma_f32_16x16x32_bf16 v[192:195], v[224:227], v[102:105], v[192:195]
	v_add_f32_e32 v130, v80, v130
	v_add_f32_e32 v131, v81, v131
	v_mfma_f32_16x16x32_bf16 v[208:211], v[224:227], v[118:121], v[208:211]
	ds_read_b128 v[224:227], v190 offset:49152
	v_add_f32_e32 v130, v130, v131
	v_mfma_f32_16x16x32_bf16 v[196:199], v[228:231], v[102:105], v[196:199]
	v_add_f32_e32 v165, v165, v130
	v_add_f32_e32 v132, v82, v83
	v_mfma_f32_16x16x32_bf16 v[212:215], v[228:231], v[118:121], v[212:215]
	ds_read_b128 v[228:231], v190 offset:53248
	v_add_f32_e32 v133, v84, v85
	s_waitcnt lgkmcnt(6)
	v_mfma_f32_16x16x32_bf16 v[200:203], v[232:235], v[102:105], v[200:203]
	v_add_f32_e32 v132, v86, v132
	v_add_f32_e32 v133, v87, v133
	v_mfma_f32_16x16x32_bf16 v[216:219], v[232:235], v[118:121], v[216:219]
	ds_read_b128 v[232:235], v190 offset:57344
	v_add_f32_e32 v132, v88, v132
	v_mfma_f32_16x16x32_bf16 v[204:207], v[236:239], v[102:105], v[204:207]
	v_add_f32_e32 v133, v89, v133
	v_add_f32_e32 v132, v90, v132
	v_mfma_f32_16x16x32_bf16 v[220:223], v[236:239], v[118:121], v[220:223]
	ds_read_b128 v[236:239], v190 offset:61440
	v_add_f32_e32 v133, v91, v133
	s_waitcnt lgkmcnt(6)
	v_mfma_f32_16x16x32_bf16 v[192:195], v[166:169], v[106:109], v[192:195]
	v_add_f32_e32 v132, v92, v132
	v_add_f32_e32 v133, v93, v133
	v_mfma_f32_16x16x32_bf16 v[208:211], v[166:169], v[122:125], v[208:211]
	ds_read_b64_tr_b16 v[166:167], v142 offset:0
	ds_read_b64_tr_b16 v[168:169], v142 offset:4096
	v_add_f32_e32 v132, v94, v132
	v_mfma_f32_16x16x32_bf16 v[196:199], v[170:173], v[106:109], v[196:199]
	v_add_f32_e32 v133, v95, v133
	v_add_f32_e32 v132, v96, v132
	v_mfma_f32_16x16x32_bf16 v[212:215], v[170:173], v[122:125], v[212:215]
	ds_read_b64_tr_b16 v[170:171], v143 offset:0
	ds_read_b64_tr_b16 v[172:173], v143 offset:4096
	v_add_f32_e32 v133, v97, v133
	s_waitcnt lgkmcnt(8)
	v_mfma_f32_16x16x32_bf16 v[200:203], v[174:177], v[106:109], v[200:203]
	v_add_f32_e32 v132, v132, v133
	v_add_f32_e32 v163, v163, v132
	v_mfma_f32_16x16x32_bf16 v[216:219], v[174:177], v[122:125], v[216:219]
	ds_read_b64_tr_b16 v[174:175], v144 offset:0
	ds_read_b64_tr_b16 v[176:177], v144 offset:4096
	v_cvt_pk_bf16_f32 v66, v66, v67
	v_mfma_f32_16x16x32_bf16 v[204:207], v[178:181], v[106:109], v[204:207]
	v_cvt_pk_bf16_f32 v67, v68, v69
	v_cvt_pk_bf16_f32 v68, v70, v71
	v_mfma_f32_16x16x32_bf16 v[220:223], v[178:181], v[122:125], v[220:223]
	ds_read_b64_tr_b16 v[178:179], v145 offset:0
	ds_read_b64_tr_b16 v[180:181], v145 offset:4096
	v_cvt_pk_bf16_f32 v69, v72, v73
	s_waitcnt lgkmcnt(10)
	v_mfma_f32_16x16x32_bf16 v[192:195], v[224:227], v[110:113], v[192:195]
	v_cvt_pk_bf16_f32 v74, v74, v75
	v_cvt_pk_bf16_f32 v75, v76, v77
	v_mfma_f32_16x16x32_bf16 v[208:211], v[224:227], v[126:129], v[208:211]
	ds_read_b64_tr_b16 v[224:225], v146 offset:0
	ds_read_b64_tr_b16 v[226:227], v146 offset:4096
	v_cvt_pk_bf16_f32 v76, v78, v79
	v_mfma_f32_16x16x32_bf16 v[196:199], v[228:231], v[110:113], v[196:199]
	v_cvt_pk_bf16_f32 v77, v80, v81
	v_cvt_pk_bf16_f32 v82, v82, v83
	v_mfma_f32_16x16x32_bf16 v[212:215], v[228:231], v[126:129], v[212:215]
	v_cvt_pk_bf16_f32 v83, v84, v85
	s_waitcnt lgkmcnt(10)
	v_mfma_f32_16x16x32_bf16 v[200:203], v[232:235], v[110:113], v[200:203]
	v_cvt_pk_bf16_f32 v84, v86, v87
	v_cvt_pk_bf16_f32 v85, v88, v89
	v_mfma_f32_16x16x32_bf16 v[216:219], v[232:235], v[126:129], v[216:219]
	v_cvt_pk_bf16_f32 v90, v90, v91
	v_mfma_f32_16x16x32_bf16 v[204:207], v[236:239], v[110:113], v[204:207]
	v_cvt_pk_bf16_f32 v91, v92, v93
	v_cvt_pk_bf16_f32 v92, v94, v95
	v_mfma_f32_16x16x32_bf16 v[220:223], v[236:239], v[126:129], v[220:223]
	v_cvt_pk_bf16_f32 v93, v96, v97
	s_waitcnt lgkmcnt(6)
	v_mfma_f32_16x16x32_bf16 v[2:5], v[66:69], v[166:169], v[2:5]
	v_mfma_f32_16x16x32_bf16 v[34:37], v[82:85], v[166:169], v[34:37]
	ds_read_b64_tr_b16 v[228:229], v147 offset:0
	ds_read_b64_tr_b16 v[230:231], v147 offset:4096
	v_mfma_f32_16x16x32_bf16 v[6:9], v[66:69], v[170:173], v[6:9]
	v_mfma_f32_16x16x32_bf16 v[38:41], v[82:85], v[170:173], v[38:41]
	ds_read_b64_tr_b16 v[232:233], v148 offset:0
	ds_read_b64_tr_b16 v[234:235], v148 offset:4096
	s_waitcnt lgkmcnt(6)
	v_mfma_f32_16x16x32_bf16 v[10:13], v[66:69], v[174:177], v[10:13]
	v_exp_f32_e32 v192, v192
	v_exp_f32_e32 v193, v193
	v_mfma_f32_16x16x32_bf16 v[42:45], v[82:85], v[174:177], v[42:45]
	ds_read_b64_tr_b16 v[236:237], v149 offset:0
	ds_read_b64_tr_b16 v[238:239], v149 offset:4096
	v_exp_f32_e32 v194, v194
	v_mfma_f32_16x16x32_bf16 v[14:17], v[66:69], v[178:181], v[14:17]
	v_exp_f32_e32 v195, v195
	v_mfma_f32_16x16x32_bf16 v[46:49], v[82:85], v[178:181], v[46:49]
	ds_read_b64_tr_b16 v[166:167], v142 offset:8192
	ds_read_b64_tr_b16 v[168:169], v142 offset:12288
	v_exp_f32_e32 v208, v208
	s_waitcnt lgkmcnt(6)
	v_mfma_f32_16x16x32_bf16 v[18:21], v[66:69], v[224:227], v[18:21]
	v_exp_f32_e32 v209, v209
	v_mfma_f32_16x16x32_bf16 v[50:53], v[82:85], v[224:227], v[50:53]
	ds_read_b64_tr_b16 v[170:171], v143 offset:8192
	ds_read_b64_tr_b16 v[172:173], v143 offset:12288
	v_exp_f32_e32 v210, v210
	v_mfma_f32_16x16x32_bf16 v[22:25], v[66:69], v[228:231], v[22:25]
	v_exp_f32_e32 v211, v211
	v_exp_f32_e32 v196, v196
	v_mfma_f32_16x16x32_bf16 v[54:57], v[82:85], v[228:231], v[54:57]
	ds_read_b64_tr_b16 v[174:175], v144 offset:8192
	ds_read_b64_tr_b16 v[176:177], v144 offset:12288
	v_exp_f32_e32 v197, v197
	s_waitcnt lgkmcnt(6)
	v_mfma_f32_16x16x32_bf16 v[26:29], v[66:69], v[232:235], v[26:29]
	v_exp_f32_e32 v198, v198
	v_mfma_f32_16x16x32_bf16 v[58:61], v[82:85], v[232:235], v[58:61]
	ds_read_b64_tr_b16 v[178:179], v145 offset:8192
	ds_read_b64_tr_b16 v[180:181], v145 offset:12288
	v_exp_f32_e32 v199, v199
	v_mfma_f32_16x16x32_bf16 v[30:33], v[66:69], v[236:239], v[30:33]
	v_exp_f32_e32 v212, v212
	v_mfma_f32_16x16x32_bf16 v[62:65], v[82:85], v[236:239], v[62:65]
	ds_read_b64_tr_b16 v[224:225], v146 offset:8192
	ds_read_b64_tr_b16 v[226:227], v146 offset:12288
	v_exp_f32_e32 v213, v213
	s_waitcnt lgkmcnt(6)
	v_mfma_f32_16x16x32_bf16 v[2:5], v[74:77], v[166:169], v[2:5]
	v_exp_f32_e32 v214, v214
	v_mfma_f32_16x16x32_bf16 v[34:37], v[90:93], v[166:169], v[34:37]
	ds_read_b64_tr_b16 v[228:229], v147 offset:8192
	ds_read_b64_tr_b16 v[230:231], v147 offset:12288
	ds_read_b128 v[166:169], v183 offset:16384
	v_exp_f32_e32 v215, v215
	v_mfma_f32_16x16x32_bf16 v[6:9], v[74:77], v[170:173], v[6:9]
	v_exp_f32_e32 v200, v200
	v_exp_f32_e32 v201, v201
	v_mfma_f32_16x16x32_bf16 v[38:41], v[90:93], v[170:173], v[38:41]
	ds_read_b64_tr_b16 v[232:233], v148 offset:8192
	ds_read_b64_tr_b16 v[234:235], v148 offset:12288
	ds_read_b128 v[170:173], v183 offset:20480
	v_exp_f32_e32 v202, v202
	s_waitcnt lgkmcnt(8)
	v_mfma_f32_16x16x32_bf16 v[10:13], v[74:77], v[174:177], v[10:13]
	v_exp_f32_e32 v203, v203
	v_mfma_f32_16x16x32_bf16 v[42:45], v[90:93], v[174:177], v[42:45]
	ds_read_b64_tr_b16 v[236:237], v149 offset:8192
	ds_read_b64_tr_b16 v[238:239], v149 offset:12288
	ds_read_b128 v[174:177], v183 offset:24576
	v_exp_f32_e32 v216, v216
	v_mfma_f32_16x16x32_bf16 v[14:17], v[74:77], v[178:181], v[14:17]
	v_exp_f32_e32 v217, v217
	v_mfma_f32_16x16x32_bf16 v[46:49], v[90:93], v[178:181], v[46:49]
	ds_read_b128 v[178:181], v183 offset:28672
	v_exp_f32_e32 v218, v218
	s_waitcnt lgkmcnt(8)
	v_mfma_f32_16x16x32_bf16 v[18:21], v[74:77], v[224:227], v[18:21]
	v_exp_f32_e32 v219, v219
	v_exp_f32_e32 v204, v204
	v_mfma_f32_16x16x32_bf16 v[50:53], v[90:93], v[224:227], v[50:53]
	ds_read_b128 v[224:227], v184 offset:16384
	v_exp_f32_e32 v205, v205
	v_mfma_f32_16x16x32_bf16 v[22:25], v[74:77], v[228:231], v[22:25]
	v_exp_f32_e32 v206, v206
	v_mfma_f32_16x16x32_bf16 v[54:57], v[90:93], v[228:231], v[54:57]
	ds_read_b128 v[228:231], v184 offset:20480
	v_exp_f32_e32 v207, v207
	s_waitcnt lgkmcnt(4)
	v_mfma_f32_16x16x32_bf16 v[26:29], v[74:77], v[232:235], v[26:29]
	v_exp_f32_e32 v220, v220
	v_mfma_f32_16x16x32_bf16 v[58:61], v[90:93], v[232:235], v[58:61]
	ds_read_b128 v[232:235], v184 offset:24576
	v_exp_f32_e32 v221, v221
	v_mfma_f32_16x16x32_bf16 v[30:33], v[74:77], v[236:239], v[30:33]
	v_exp_f32_e32 v222, v222
	v_mfma_f32_16x16x32_bf16 v[62:65], v[90:93], v[236:239], v[62:65]
	ds_read_b128 v[236:239], v184 offset:28672
	v_exp_f32_e32 v223, v223
	s_waitcnt vmcnt(0)
	s_barrier
	v_mfma_f32_16x16x32_bf16 v[66:69], v[166:169], v[98:101], 0
	v_add_f32_e32 v130, v192, v193
	v_add_f32_e32 v131, v194, v195
	v_mfma_f32_16x16x32_bf16 v[82:85], v[166:169], v[114:117], 0
	ds_read_b128 v[166:169], v185 offset:16384
	s_add_i32 m0, s45, 0x10000
	v_add_f32_e32 v130, v196, v130
	global_load_lds_dwordx4 v152, s[64:65]
	v_mfma_f32_16x16x32_bf16 v[70:73], v[170:173], v[98:101], 0
	v_add_f32_e32 v131, v197, v131
	v_add_f32_e32 v130, v198, v130
	v_mfma_f32_16x16x32_bf16 v[86:89], v[170:173], v[114:117], 0
	ds_read_b128 v[170:173], v185 offset:20480
	s_add_i32 m0, s45, 0x14000
	v_add_f32_e32 v131, v199, v131
	global_load_lds_dwordx4 v150, s[62:63]
	s_waitcnt lgkmcnt(6)
	v_mfma_f32_16x16x32_bf16 v[74:77], v[174:177], v[98:101], 0
	v_add_f32_e32 v130, v200, v130
	v_add_f32_e32 v131, v201, v131
	v_mfma_f32_16x16x32_bf16 v[90:93], v[174:177], v[114:117], 0
	ds_read_b128 v[174:177], v185 offset:24576
	s_add_i32 m0, s45, 0x12000
	v_add_f32_e32 v130, v202, v130
	global_load_lds_dwordx4 v153, s[64:65]
	v_mfma_f32_16x16x32_bf16 v[78:81], v[178:181], v[98:101], 0
	v_add_f32_e32 v131, v203, v131
	v_add_f32_e32 v130, v204, v130
	v_mfma_f32_16x16x32_bf16 v[94:97], v[178:181], v[114:117], 0
	ds_read_b128 v[178:181], v185 offset:28672
	s_add_i32 m0, s45, 0x16000
	v_add_f32_e32 v131, v205, v131
	global_load_lds_dwordx4 v151, s[62:63]
	s_add_u32 s62, s62, 0x4000
	s_addc_u32 s63, s63, 0
	s_add_u32 s64, s64, 0x4000
	s_addc_u32 s65, s65, 0
	s_waitcnt lgkmcnt(6)
	v_mfma_f32_16x16x32_bf16 v[66:69], v[224:227], v[102:105], v[66:69]
	v_add_f32_e32 v130, v206, v130
	v_add_f32_e32 v131, v207, v131
	v_mfma_f32_16x16x32_bf16 v[82:85], v[224:227], v[118:121], v[82:85]
	ds_read_b128 v[224:227], v186 offset:16384
	v_add_f32_e32 v130, v130, v131
	v_mfma_f32_16x16x32_bf16 v[70:73], v[228:231], v[102:105], v[70:73]
	v_add_f32_e32 v165, v165, v130
	v_add_f32_e32 v132, v208, v209
	v_mfma_f32_16x16x32_bf16 v[86:89], v[228:231], v[118:121], v[86:89]
	ds_read_b128 v[228:231], v186 offset:20480
	v_add_f32_e32 v133, v210, v211
	s_waitcnt lgkmcnt(6)
	v_mfma_f32_16x16x32_bf16 v[74:77], v[232:235], v[102:105], v[74:77]
	v_add_f32_e32 v132, v212, v132
	v_add_f32_e32 v133, v213, v133
	v_mfma_f32_16x16x32_bf16 v[90:93], v[232:235], v[118:121], v[90:93]
	ds_read_b128 v[232:235], v186 offset:24576
	v_add_f32_e32 v132, v214, v132
	v_mfma_f32_16x16x32_bf16 v[78:81], v[236:239], v[102:105], v[78:81]
	v_add_f32_e32 v133, v215, v133
	v_add_f32_e32 v132, v216, v132
	v_mfma_f32_16x16x32_bf16 v[94:97], v[236:239], v[118:121], v[94:97]
	ds_read_b128 v[236:239], v186 offset:28672
	v_add_f32_e32 v133, v217, v133
	s_waitcnt lgkmcnt(6)
	v_mfma_f32_16x16x32_bf16 v[66:69], v[166:169], v[106:109], v[66:69]
	v_add_f32_e32 v132, v218, v132
	v_add_f32_e32 v133, v219, v133
	v_mfma_f32_16x16x32_bf16 v[82:85], v[166:169], v[122:125], v[82:85]
	ds_read_b64_tr_b16 v[166:167], v142 offset:32768
	ds_read_b64_tr_b16 v[168:169], v142 offset:36864
	v_add_f32_e32 v132, v220, v132
	v_mfma_f32_16x16x32_bf16 v[70:73], v[170:173], v[106:109], v[70:73]
	v_add_f32_e32 v133, v221, v133
	v_add_f32_e32 v132, v222, v132
	v_mfma_f32_16x16x32_bf16 v[86:89], v[170:173], v[122:125], v[86:89]
	ds_read_b64_tr_b16 v[170:171], v143 offset:32768
	ds_read_b64_tr_b16 v[172:173], v143 offset:36864
	v_add_f32_e32 v133, v223, v133
	s_waitcnt lgkmcnt(8)
	v_mfma_f32_16x16x32_bf16 v[74:77], v[174:177], v[106:109], v[74:77]
	v_add_f32_e32 v132, v132, v133
	v_add_f32_e32 v163, v163, v132
	v_mfma_f32_16x16x32_bf16 v[90:93], v[174:177], v[122:125], v[90:93]
	ds_read_b64_tr_b16 v[174:175], v144 offset:32768
	ds_read_b64_tr_b16 v[176:177], v144 offset:36864
	v_cvt_pk_bf16_f32 v192, v192, v193
	v_mfma_f32_16x16x32_bf16 v[78:81], v[178:181], v[106:109], v[78:81]
	v_cvt_pk_bf16_f32 v193, v194, v195
	v_cvt_pk_bf16_f32 v194, v196, v197
	v_mfma_f32_16x16x32_bf16 v[94:97], v[178:181], v[122:125], v[94:97]
	ds_read_b64_tr_b16 v[178:179], v145 offset:32768
	ds_read_b64_tr_b16 v[180:181], v145 offset:36864
	v_cvt_pk_bf16_f32 v195, v198, v199
	s_waitcnt lgkmcnt(10)
	v_mfma_f32_16x16x32_bf16 v[66:69], v[224:227], v[110:113], v[66:69]
	v_cvt_pk_bf16_f32 v200, v200, v201
	v_cvt_pk_bf16_f32 v201, v202, v203
	v_mfma_f32_16x16x32_bf16 v[82:85], v[224:227], v[126:129], v[82:85]
	ds_read_b64_tr_b16 v[224:225], v146 offset:32768
	ds_read_b64_tr_b16 v[226:227], v146 offset:36864
	v_cvt_pk_bf16_f32 v202, v204, v205
	v_mfma_f32_16x16x32_bf16 v[70:73], v[228:231], v[110:113], v[70:73]
	v_cvt_pk_bf16_f32 v203, v206, v207
	v_cvt_pk_bf16_f32 v208, v208, v209
	v_mfma_f32_16x16x32_bf16 v[86:89], v[228:231], v[126:129], v[86:89]
	v_cvt_pk_bf16_f32 v209, v210, v211
	s_waitcnt lgkmcnt(10)
	v_mfma_f32_16x16x32_bf16 v[74:77], v[232:235], v[110:113], v[74:77]
	v_cvt_pk_bf16_f32 v210, v212, v213
	v_cvt_pk_bf16_f32 v211, v214, v215
	v_mfma_f32_16x16x32_bf16 v[90:93], v[232:235], v[126:129], v[90:93]
	v_cvt_pk_bf16_f32 v216, v216, v217
	v_mfma_f32_16x16x32_bf16 v[78:81], v[236:239], v[110:113], v[78:81]
	v_cvt_pk_bf16_f32 v217, v218, v219
	v_cvt_pk_bf16_f32 v218, v220, v221
	v_mfma_f32_16x16x32_bf16 v[94:97], v[236:239], v[126:129], v[94:97]
	v_cvt_pk_bf16_f32 v219, v222, v223
	s_waitcnt lgkmcnt(6)
	v_mfma_f32_16x16x32_bf16 v[2:5], v[192:195], v[166:169], v[2:5]
	v_mfma_f32_16x16x32_bf16 v[34:37], v[208:211], v[166:169], v[34:37]
	ds_read_b64_tr_b16 v[228:229], v147 offset:32768
	ds_read_b64_tr_b16 v[230:231], v147 offset:36864
	v_mfma_f32_16x16x32_bf16 v[6:9], v[192:195], v[170:173], v[6:9]
	v_mfma_f32_16x16x32_bf16 v[38:41], v[208:211], v[170:173], v[38:41]
	ds_read_b64_tr_b16 v[232:233], v148 offset:32768
	ds_read_b64_tr_b16 v[234:235], v148 offset:36864
	s_waitcnt lgkmcnt(6)
	v_mfma_f32_16x16x32_bf16 v[10:13], v[192:195], v[174:177], v[10:13]
	v_exp_f32_e32 v66, v66
	v_exp_f32_e32 v67, v67
	v_mfma_f32_16x16x32_bf16 v[42:45], v[208:211], v[174:177], v[42:45]
	ds_read_b64_tr_b16 v[236:237], v149 offset:32768
	ds_read_b64_tr_b16 v[238:239], v149 offset:36864
	v_exp_f32_e32 v68, v68
	v_mfma_f32_16x16x32_bf16 v[14:17], v[192:195], v[178:181], v[14:17]
	v_exp_f32_e32 v69, v69
	v_mfma_f32_16x16x32_bf16 v[46:49], v[208:211], v[178:181], v[46:49]
	ds_read_b64_tr_b16 v[166:167], v142 offset:40960
	ds_read_b64_tr_b16 v[168:169], v142 offset:45056
	v_exp_f32_e32 v82, v82
	s_waitcnt lgkmcnt(6)
	v_mfma_f32_16x16x32_bf16 v[18:21], v[192:195], v[224:227], v[18:21]
	v_exp_f32_e32 v83, v83
	v_mfma_f32_16x16x32_bf16 v[50:53], v[208:211], v[224:227], v[50:53]
	ds_read_b64_tr_b16 v[170:171], v143 offset:40960
	ds_read_b64_tr_b16 v[172:173], v143 offset:45056
	v_exp_f32_e32 v84, v84
	v_mfma_f32_16x16x32_bf16 v[22:25], v[192:195], v[228:231], v[22:25]
	v_exp_f32_e32 v85, v85
	v_exp_f32_e32 v70, v70
	v_mfma_f32_16x16x32_bf16 v[54:57], v[208:211], v[228:231], v[54:57]
	ds_read_b64_tr_b16 v[174:175], v144 offset:40960
	ds_read_b64_tr_b16 v[176:177], v144 offset:45056
	v_exp_f32_e32 v71, v71
	s_waitcnt lgkmcnt(6)
	v_mfma_f32_16x16x32_bf16 v[26:29], v[192:195], v[232:235], v[26:29]
	v_exp_f32_e32 v72, v72
	v_mfma_f32_16x16x32_bf16 v[58:61], v[208:211], v[232:235], v[58:61]
	ds_read_b64_tr_b16 v[178:179], v145 offset:40960
	ds_read_b64_tr_b16 v[180:181], v145 offset:45056
	v_exp_f32_e32 v73, v73
	v_mfma_f32_16x16x32_bf16 v[30:33], v[192:195], v[236:239], v[30:33]
	v_exp_f32_e32 v86, v86
	v_mfma_f32_16x16x32_bf16 v[62:65], v[208:211], v[236:239], v[62:65]
	ds_read_b64_tr_b16 v[224:225], v146 offset:40960
	ds_read_b64_tr_b16 v[226:227], v146 offset:45056
	v_exp_f32_e32 v87, v87
	s_waitcnt lgkmcnt(6)
	v_mfma_f32_16x16x32_bf16 v[2:5], v[200:203], v[166:169], v[2:5]
	v_exp_f32_e32 v88, v88
	v_mfma_f32_16x16x32_bf16 v[34:37], v[216:219], v[166:169], v[34:37]
	ds_read_b64_tr_b16 v[228:229], v147 offset:40960
	ds_read_b64_tr_b16 v[230:231], v147 offset:45056
	ds_read_b128 v[166:169], v183 offset:49152
	v_exp_f32_e32 v89, v89
	v_mfma_f32_16x16x32_bf16 v[6:9], v[200:203], v[170:173], v[6:9]
	v_exp_f32_e32 v74, v74
	v_exp_f32_e32 v75, v75
	v_mfma_f32_16x16x32_bf16 v[38:41], v[216:219], v[170:173], v[38:41]
	ds_read_b64_tr_b16 v[232:233], v148 offset:40960
	ds_read_b64_tr_b16 v[234:235], v148 offset:45056
	ds_read_b128 v[170:173], v183 offset:53248
	v_exp_f32_e32 v76, v76
	s_waitcnt lgkmcnt(8)
	v_mfma_f32_16x16x32_bf16 v[10:13], v[200:203], v[174:177], v[10:13]
	v_exp_f32_e32 v77, v77
	v_mfma_f32_16x16x32_bf16 v[42:45], v[216:219], v[174:177], v[42:45]
	ds_read_b64_tr_b16 v[236:237], v149 offset:40960
	ds_read_b64_tr_b16 v[238:239], v149 offset:45056
	ds_read_b128 v[174:177], v183 offset:57344
	v_exp_f32_e32 v90, v90
	v_mfma_f32_16x16x32_bf16 v[14:17], v[200:203], v[178:181], v[14:17]
	v_exp_f32_e32 v91, v91
	v_mfma_f32_16x16x32_bf16 v[46:49], v[216:219], v[178:181], v[46:49]
	ds_read_b128 v[178:181], v183 offset:61440
	v_exp_f32_e32 v92, v92
	s_waitcnt lgkmcnt(8)
	v_mfma_f32_16x16x32_bf16 v[18:21], v[200:203], v[224:227], v[18:21]
	v_exp_f32_e32 v93, v93
	v_exp_f32_e32 v78, v78
	v_mfma_f32_16x16x32_bf16 v[50:53], v[216:219], v[224:227], v[50:53]
	ds_read_b128 v[224:227], v184 offset:49152
	v_exp_f32_e32 v79, v79
	v_mfma_f32_16x16x32_bf16 v[22:25], v[200:203], v[228:231], v[22:25]
	v_exp_f32_e32 v80, v80
	v_mfma_f32_16x16x32_bf16 v[54:57], v[216:219], v[228:231], v[54:57]
	ds_read_b128 v[228:231], v184 offset:53248
	v_exp_f32_e32 v81, v81
	s_waitcnt lgkmcnt(4)
	v_mfma_f32_16x16x32_bf16 v[26:29], v[200:203], v[232:235], v[26:29]
	v_exp_f32_e32 v94, v94
	v_mfma_f32_16x16x32_bf16 v[58:61], v[216:219], v[232:235], v[58:61]
	ds_read_b128 v[232:235], v184 offset:57344
	v_exp_f32_e32 v95, v95
	v_mfma_f32_16x16x32_bf16 v[30:33], v[200:203], v[236:239], v[30:33]
	v_exp_f32_e32 v96, v96
	v_mfma_f32_16x16x32_bf16 v[62:65], v[216:219], v[236:239], v[62:65]
	ds_read_b128 v[236:239], v184 offset:61440
	v_exp_f32_e32 v97, v97
	s_waitcnt vmcnt(0)
	s_barrier
	s_sub_u32 s66, s66, 1
	s_cmp_lg_u32 s66, 0
	s_cbranch_scc1 .Lattn_loop
	v_mfma_f32_16x16x32_bf16 v[192:195], v[166:169], v[98:101], 0
	v_add_f32_e32 v130, v66, v67
	v_add_f32_e32 v131, v68, v69
	v_mfma_f32_16x16x32_bf16 v[208:211], v[166:169], v[114:117], 0
	ds_read_b128 v[166:169], v185 offset:49152
	s_add_i32 m0, s45, 0x18000
	v_add_f32_e32 v130, v70, v130
	global_load_lds_dwordx4 v152, s[64:65]
	v_mfma_f32_16x16x32_bf16 v[196:199], v[170:173], v[98:101], 0
	v_add_f32_e32 v131, v71, v131
	v_add_f32_e32 v130, v72, v130
	v_mfma_f32_16x16x32_bf16 v[212:215], v[170:173], v[114:117], 0
	ds_read_b128 v[170:173], v185 offset:53248
	s_add_i32 m0, s45, 0x1c000
	v_add_f32_e32 v131, v73, v131
	global_load_lds_dwordx4 v150, s[62:63]
	s_waitcnt lgkmcnt(6)
	v_mfma_f32_16x16x32_bf16 v[200:203], v[174:177], v[98:101], 0
	v_add_f32_e32 v130, v74, v130
	v_add_f32_e32 v131, v75, v131
	v_mfma_f32_16x16x32_bf16 v[216:219], v[174:177], v[114:117], 0
	ds_read_b128 v[174:177], v185 offset:57344
	s_add_i32 m0, s45, 0x1a000
	v_add_f32_e32 v130, v76, v130
	global_load_lds_dwordx4 v153, s[64:65]
	v_mfma_f32_16x16x32_bf16 v[204:207], v[178:181], v[98:101], 0
	v_add_f32_e32 v131, v77, v131
	v_add_f32_e32 v130, v78, v130
	v_mfma_f32_16x16x32_bf16 v[220:223], v[178:181], v[114:117], 0
	ds_read_b128 v[178:181], v185 offset:61440
	s_add_i32 m0, s45, 0x1e000
	v_add_f32_e32 v131, v79, v131
	global_load_lds_dwordx4 v151, s[62:63]
	s_add_u32 s62, s62, 0x4000
	s_addc_u32 s63, s63, 0
	s_add_u32 s64, s64, 0x4000
	s_addc_u32 s65, s65, 0
	s_waitcnt lgkmcnt(6)
	v_mfma_f32_16x16x32_bf16 v[192:195], v[224:227], v[102:105], v[192:195]
	v_add_f32_e32 v130, v80, v130
	v_add_f32_e32 v131, v81, v131
	v_mfma_f32_16x16x32_bf16 v[208:211], v[224:227], v[118:121], v[208:211]
	ds_read_b128 v[224:227], v186 offset:49152
	v_add_f32_e32 v130, v130, v131
	v_mfma_f32_16x16x32_bf16 v[196:199], v[228:231], v[102:105], v[196:199]
	v_add_f32_e32 v165, v165, v130
	v_add_f32_e32 v132, v82, v83
	v_mfma_f32_16x16x32_bf16 v[212:215], v[228:231], v[118:121], v[212:215]
	ds_read_b128 v[228:231], v186 offset:53248
	v_add_f32_e32 v133, v84, v85
	s_waitcnt lgkmcnt(6)
	v_mfma_f32_16x16x32_bf16 v[200:203], v[232:235], v[102:105], v[200:203]
	v_add_f32_e32 v132, v86, v132
	v_add_f32_e32 v133, v87, v133
	v_mfma_f32_16x16x32_bf16 v[216:219], v[232:235], v[118:121], v[216:219]
	ds_read_b128 v[232:235], v186 offset:57344
	v_add_f32_e32 v132, v88, v132
	v_mfma_f32_16x16x32_bf16 v[204:207], v[236:239], v[102:105], v[204:207]
	v_add_f32_e32 v133, v89, v133
	v_add_f32_e32 v132, v90, v132
	v_mfma_f32_16x16x32_bf16 v[220:223], v[236:239], v[118:121], v[220:223]
	ds_read_b128 v[236:239], v186 offset:61440
	v_add_f32_e32 v133, v91, v133
	s_waitcnt lgkmcnt(6)
	v_mfma_f32_16x16x32_bf16 v[192:195], v[166:169], v[106:109], v[192:195]
	v_add_f32_e32 v132, v92, v132
	v_add_f32_e32 v133, v93, v133
	v_mfma_f32_16x16x32_bf16 v[208:211], v[166:169], v[122:125], v[208:211]
	ds_read_b64_tr_b16 v[166:167], v240 offset:0
	ds_read_b64_tr_b16 v[168:169], v240 offset:4096
	v_add_f32_e32 v132, v94, v132
	v_mfma_f32_16x16x32_bf16 v[196:199], v[170:173], v[106:109], v[196:199]
	v_add_f32_e32 v133, v95, v133
	v_add_f32_e32 v132, v96, v132
	v_mfma_f32_16x16x32_bf16 v[212:215], v[170:173], v[122:125], v[212:215]
	ds_read_b64_tr_b16 v[170:171], v241 offset:0
	ds_read_b64_tr_b16 v[172:173], v241 offset:4096
	v_add_f32_e32 v133, v97, v133
	s_waitcnt lgkmcnt(8)
	v_mfma_f32_16x16x32_bf16 v[200:203], v[174:177], v[106:109], v[200:203]
	v_add_f32_e32 v132, v132, v133
	v_add_f32_e32 v163, v163, v132
	v_mfma_f32_16x16x32_bf16 v[216:219], v[174:177], v[122:125], v[216:219]
	ds_read_b64_tr_b16 v[174:175], v242 offset:0
	ds_read_b64_tr_b16 v[176:177], v242 offset:4096
	v_cvt_pk_bf16_f32 v66, v66, v67
	v_mfma_f32_16x16x32_bf16 v[204:207], v[178:181], v[106:109], v[204:207]
	v_cvt_pk_bf16_f32 v67, v68, v69
	v_cvt_pk_bf16_f32 v68, v70, v71
	v_mfma_f32_16x16x32_bf16 v[220:223], v[178:181], v[122:125], v[220:223]
	ds_read_b64_tr_b16 v[178:179], v243 offset:0
	ds_read_b64_tr_b16 v[180:181], v243 offset:4096
	v_cvt_pk_bf16_f32 v69, v72, v73
	s_waitcnt lgkmcnt(10)
	v_mfma_f32_16x16x32_bf16 v[192:195], v[224:227], v[110:113], v[192:195]
	v_cvt_pk_bf16_f32 v74, v74, v75
	v_cvt_pk_bf16_f32 v75, v76, v77
	v_mfma_f32_16x16x32_bf16 v[208:211], v[224:227], v[126:129], v[208:211]
	ds_read_b64_tr_b16 v[224:225], v244 offset:0
	ds_read_b64_tr_b16 v[226:227], v244 offset:4096
	v_cvt_pk_bf16_f32 v76, v78, v79
	v_mfma_f32_16x16x32_bf16 v[196:199], v[228:231], v[110:113], v[196:199]
	v_cvt_pk_bf16_f32 v77, v80, v81
	v_cvt_pk_bf16_f32 v82, v82, v83
	v_mfma_f32_16x16x32_bf16 v[212:215], v[228:231], v[126:129], v[212:215]
	v_cvt_pk_bf16_f32 v83, v84, v85
	s_waitcnt lgkmcnt(10)
	v_mfma_f32_16x16x32_bf16 v[200:203], v[232:235], v[110:113], v[200:203]
	v_cvt_pk_bf16_f32 v84, v86, v87
	v_cvt_pk_bf16_f32 v85, v88, v89
	v_mfma_f32_16x16x32_bf16 v[216:219], v[232:235], v[126:129], v[216:219]
	v_cvt_pk_bf16_f32 v90, v90, v91
	v_mfma_f32_16x16x32_bf16 v[204:207], v[236:239], v[110:113], v[204:207]
	v_cvt_pk_bf16_f32 v91, v92, v93
	v_cvt_pk_bf16_f32 v92, v94, v95
	v_mfma_f32_16x16x32_bf16 v[220:223], v[236:239], v[126:129], v[220:223]
	v_cvt_pk_bf16_f32 v93, v96, v97
	s_waitcnt lgkmcnt(6)
	v_mfma_f32_16x16x32_bf16 v[2:5], v[66:69], v[166:169], v[2:5]
	v_mfma_f32_16x16x32_bf16 v[34:37], v[82:85], v[166:169], v[34:37]
	ds_read_b64_tr_b16 v[228:229], v245 offset:0
	ds_read_b64_tr_b16 v[230:231], v245 offset:4096
	v_mfma_f32_16x16x32_bf16 v[6:9], v[66:69], v[170:173], v[6:9]
	v_mfma_f32_16x16x32_bf16 v[38:41], v[82:85], v[170:173], v[38:41]
	ds_read_b64_tr_b16 v[232:233], v246 offset:0
	ds_read_b64_tr_b16 v[234:235], v246 offset:4096
	s_waitcnt lgkmcnt(6)
	v_mfma_f32_16x16x32_bf16 v[10:13], v[66:69], v[174:177], v[10:13]
	v_exp_f32_e32 v192, v192
	v_exp_f32_e32 v193, v193
	v_mfma_f32_16x16x32_bf16 v[42:45], v[82:85], v[174:177], v[42:45]
	ds_read_b64_tr_b16 v[236:237], v247 offset:0
	ds_read_b64_tr_b16 v[238:239], v247 offset:4096
	v_exp_f32_e32 v194, v194
	v_mfma_f32_16x16x32_bf16 v[14:17], v[66:69], v[178:181], v[14:17]
	v_exp_f32_e32 v195, v195
	v_mfma_f32_16x16x32_bf16 v[46:49], v[82:85], v[178:181], v[46:49]
	ds_read_b64_tr_b16 v[166:167], v240 offset:8192
	ds_read_b64_tr_b16 v[168:169], v240 offset:12288
	v_exp_f32_e32 v208, v208
	s_waitcnt lgkmcnt(6)
	v_mfma_f32_16x16x32_bf16 v[18:21], v[66:69], v[224:227], v[18:21]
	v_exp_f32_e32 v209, v209
	v_mfma_f32_16x16x32_bf16 v[50:53], v[82:85], v[224:227], v[50:53]
	ds_read_b64_tr_b16 v[170:171], v241 offset:8192
	ds_read_b64_tr_b16 v[172:173], v241 offset:12288
	v_exp_f32_e32 v210, v210
	v_mfma_f32_16x16x32_bf16 v[22:25], v[66:69], v[228:231], v[22:25]
	v_exp_f32_e32 v211, v211
	v_exp_f32_e32 v196, v196
	v_mfma_f32_16x16x32_bf16 v[54:57], v[82:85], v[228:231], v[54:57]
	ds_read_b64_tr_b16 v[174:175], v242 offset:8192
	ds_read_b64_tr_b16 v[176:177], v242 offset:12288
	v_exp_f32_e32 v197, v197
	s_waitcnt lgkmcnt(6)
	v_mfma_f32_16x16x32_bf16 v[26:29], v[66:69], v[232:235], v[26:29]
	v_exp_f32_e32 v198, v198
	v_mfma_f32_16x16x32_bf16 v[58:61], v[82:85], v[232:235], v[58:61]
	ds_read_b64_tr_b16 v[178:179], v243 offset:8192
	ds_read_b64_tr_b16 v[180:181], v243 offset:12288
	v_exp_f32_e32 v199, v199
	v_mfma_f32_16x16x32_bf16 v[30:33], v[66:69], v[236:239], v[30:33]
	v_exp_f32_e32 v212, v212
	v_mfma_f32_16x16x32_bf16 v[62:65], v[82:85], v[236:239], v[62:65]
	ds_read_b64_tr_b16 v[224:225], v244 offset:8192
	ds_read_b64_tr_b16 v[226:227], v244 offset:12288
	v_exp_f32_e32 v213, v213
	s_waitcnt lgkmcnt(6)
	v_mfma_f32_16x16x32_bf16 v[2:5], v[74:77], v[166:169], v[2:5]
	v_exp_f32_e32 v214, v214
	v_mfma_f32_16x16x32_bf16 v[34:37], v[90:93], v[166:169], v[34:37]
	ds_read_b64_tr_b16 v[228:229], v245 offset:8192
	ds_read_b64_tr_b16 v[230:231], v245 offset:12288
	ds_read_b128 v[166:169], v187 offset:16384
	v_exp_f32_e32 v215, v215
	v_mfma_f32_16x16x32_bf16 v[6:9], v[74:77], v[170:173], v[6:9]
	v_exp_f32_e32 v200, v200
	v_exp_f32_e32 v201, v201
	v_mfma_f32_16x16x32_bf16 v[38:41], v[90:93], v[170:173], v[38:41]
	ds_read_b64_tr_b16 v[232:233], v246 offset:8192
	ds_read_b64_tr_b16 v[234:235], v246 offset:12288
	ds_read_b128 v[170:173], v187 offset:20480
	v_exp_f32_e32 v202, v202
	s_waitcnt lgkmcnt(8)
	v_mfma_f32_16x16x32_bf16 v[10:13], v[74:77], v[174:177], v[10:13]
	v_exp_f32_e32 v203, v203
	v_mfma_f32_16x16x32_bf16 v[42:45], v[90:93], v[174:177], v[42:45]
	ds_read_b64_tr_b16 v[236:237], v247 offset:8192
	ds_read_b64_tr_b16 v[238:239], v247 offset:12288
	ds_read_b128 v[174:177], v187 offset:24576
	v_exp_f32_e32 v216, v216
	v_mfma_f32_16x16x32_bf16 v[14:17], v[74:77], v[178:181], v[14:17]
	v_exp_f32_e32 v217, v217
	v_mfma_f32_16x16x32_bf16 v[46:49], v[90:93], v[178:181], v[46:49]
	ds_read_b128 v[178:181], v187 offset:28672
	v_exp_f32_e32 v218, v218
	s_waitcnt lgkmcnt(8)
	v_mfma_f32_16x16x32_bf16 v[18:21], v[74:77], v[224:227], v[18:21]
	v_exp_f32_e32 v219, v219
	v_exp_f32_e32 v204, v204
	v_mfma_f32_16x16x32_bf16 v[50:53], v[90:93], v[224:227], v[50:53]
	ds_read_b128 v[224:227], v188 offset:16384
	v_exp_f32_e32 v205, v205
	v_mfma_f32_16x16x32_bf16 v[22:25], v[74:77], v[228:231], v[22:25]
	v_exp_f32_e32 v206, v206
	v_mfma_f32_16x16x32_bf16 v[54:57], v[90:93], v[228:231], v[54:57]
	ds_read_b128 v[228:231], v188 offset:20480
	v_exp_f32_e32 v207, v207
	s_waitcnt lgkmcnt(4)
	v_mfma_f32_16x16x32_bf16 v[26:29], v[74:77], v[232:235], v[26:29]
	v_exp_f32_e32 v220, v220
	v_mfma_f32_16x16x32_bf16 v[58:61], v[90:93], v[232:235], v[58:61]
	ds_read_b128 v[232:235], v188 offset:24576
	v_exp_f32_e32 v221, v221
	v_mfma_f32_16x16x32_bf16 v[30:33], v[74:77], v[236:239], v[30:33]
	v_exp_f32_e32 v222, v222
	v_mfma_f32_16x16x32_bf16 v[62:65], v[90:93], v[236:239], v[62:65]
	ds_read_b128 v[236:239], v188 offset:28672
	v_exp_f32_e32 v223, v223
	s_waitcnt vmcnt(0)
	s_barrier
	s_add_i32 s66, s3, s33
	s_cmpk_lt_i32 s66, 0x400
	s_cselect_b32 s66, s66, s3
	s_lshr_b32 s0, s66, 7
	s_lshl_b32 s0, s0, 23
	s_and_b32 s1, s66, 15
	s_lshl_b32 s1, s1, 19
	s_or_b32 s0, s0, s1
	s_bfe_u32 s1, s66, 0x30004
	s_lshl_b32 s1, s1, 8
	s_or_b32 s0, s0, s1
	s_add_u32 s60, s25, s0
	s_addc_u32 s61, s28, 0
	s_add_u32 s18, s21, s0
	s_addc_u32 s19, s24, 0
	s_lshr_b32 s1, s66, 6
	s_mul_i32 s1, s1, 0x110000
	s_add_u32 s62, s9, s1
	s_addc_u32 s63, s20, 0
	s_add_u32 s64, s29, s1
	s_addc_u32 s65, s30, 0
	v_mfma_f32_16x16x32_bf16 v[66:69], v[166:169], v[98:101], 0
	v_add_f32_e32 v130, v192, v193
	v_add_f32_e32 v131, v194, v195
	v_mfma_f32_16x16x32_bf16 v[82:85], v[166:169], v[114:117], 0
	ds_read_b128 v[166:169], v189 offset:16384
	v_add_f32_e32 v130, v196, v130
	v_mfma_f32_16x16x32_bf16 v[70:73], v[170:173], v[98:101], 0
	v_add_f32_e32 v131, v197, v131
	v_add_f32_e32 v130, v198, v130
	v_mfma_f32_16x16x32_bf16 v[86:89], v[170:173], v[114:117], 0
	ds_read_b128 v[170:173], v189 offset:20480
	v_add_f32_e32 v131, v199, v131
	s_waitcnt lgkmcnt(6)
	v_mfma_f32_16x16x32_bf16 v[74:77], v[174:177], v[98:101], 0
	v_add_f32_e32 v130, v200, v130
	v_add_f32_e32 v131, v201, v131
	v_mfma_f32_16x16x32_bf16 v[90:93], v[174:177], v[114:117], 0
	ds_read_b128 v[174:177], v189 offset:24576
	v_add_f32_e32 v130, v202, v130
	v_mfma_f32_16x16x32_bf16 v[78:81], v[178:181], v[98:101], 0
	v_add_f32_e32 v131, v203, v131
	v_add_f32_e32 v130, v204, v130
	v_mfma_f32_16x16x32_bf16 v[94:97], v[178:181], v[114:117], 0
	ds_read_b128 v[178:181], v189 offset:28672
	v_add_f32_e32 v131, v205, v131
	s_waitcnt lgkmcnt(6)
	v_mfma_f32_16x16x32_bf16 v[66:69], v[224:227], v[102:105], v[66:69]
	v_add_f32_e32 v130, v206, v130
	v_add_f32_e32 v131, v207, v131
	v_mfma_f32_16x16x32_bf16 v[82:85], v[224:227], v[118:121], v[82:85]
	ds_read_b128 v[224:227], v190 offset:16384
	v_add_f32_e32 v130, v130, v131
	v_mfma_f32_16x16x32_bf16 v[70:73], v[228:231], v[102:105], v[70:73]
	v_add_f32_e32 v165, v165, v130
	v_add_f32_e32 v132, v208, v209
	v_mfma_f32_16x16x32_bf16 v[86:89], v[228:231], v[118:121], v[86:89]
	ds_read_b128 v[228:231], v190 offset:20480
	v_add_f32_e32 v133, v210, v211
	s_waitcnt lgkmcnt(6)
	v_mfma_f32_16x16x32_bf16 v[74:77], v[232:235], v[102:105], v[74:77]
	v_add_f32_e32 v132, v212, v132
	v_add_f32_e32 v133, v213, v133
	v_mfma_f32_16x16x32_bf16 v[90:93], v[232:235], v[118:121], v[90:93]
	ds_read_b128 v[232:235], v190 offset:24576
	v_add_f32_e32 v132, v214, v132
	v_mfma_f32_16x16x32_bf16 v[78:81], v[236:239], v[102:105], v[78:81]
	v_add_f32_e32 v133, v215, v133
	v_add_f32_e32 v132, v216, v132
	v_mfma_f32_16x16x32_bf16 v[94:97], v[236:239], v[118:121], v[94:97]
	ds_read_b128 v[236:239], v190 offset:28672
	v_add_f32_e32 v133, v217, v133
	s_waitcnt lgkmcnt(6)
	v_mfma_f32_16x16x32_bf16 v[66:69], v[166:169], v[106:109], v[66:69]
	v_add_f32_e32 v132, v218, v132
	v_add_f32_e32 v133, v219, v133
	v_mfma_f32_16x16x32_bf16 v[82:85], v[166:169], v[122:125], v[82:85]
	ds_read_b64_tr_b16 v[166:167], v240 offset:32768
	ds_read_b64_tr_b16 v[168:169], v240 offset:36864
	v_add_f32_e32 v132, v220, v132
	v_mfma_f32_16x16x32_bf16 v[70:73], v[170:173], v[106:109], v[70:73]
	v_add_f32_e32 v133, v221, v133
	v_add_f32_e32 v132, v222, v132
	v_mfma_f32_16x16x32_bf16 v[86:89], v[170:173], v[122:125], v[86:89]
	ds_read_b64_tr_b16 v[170:171], v241 offset:32768
	ds_read_b64_tr_b16 v[172:173], v241 offset:36864
	v_add_f32_e32 v133, v223, v133
	s_waitcnt lgkmcnt(8)
	v_mfma_f32_16x16x32_bf16 v[74:77], v[174:177], v[106:109], v[74:77]
	v_add_f32_e32 v132, v132, v133
	v_add_f32_e32 v163, v163, v132
	v_mfma_f32_16x16x32_bf16 v[90:93], v[174:177], v[122:125], v[90:93]
	ds_read_b64_tr_b16 v[174:175], v242 offset:32768
	ds_read_b64_tr_b16 v[176:177], v242 offset:36864
	v_cvt_pk_bf16_f32 v192, v192, v193
	v_mfma_f32_16x16x32_bf16 v[78:81], v[178:181], v[106:109], v[78:81]
	v_cvt_pk_bf16_f32 v193, v194, v195
	v_cvt_pk_bf16_f32 v194, v196, v197
	v_mfma_f32_16x16x32_bf16 v[94:97], v[178:181], v[122:125], v[94:97]
	ds_read_b64_tr_b16 v[178:179], v243 offset:32768
	ds_read_b64_tr_b16 v[180:181], v243 offset:36864
	v_cvt_pk_bf16_f32 v195, v198, v199
	s_waitcnt lgkmcnt(10)
	v_mfma_f32_16x16x32_bf16 v[66:69], v[224:227], v[110:113], v[66:69]
	v_cvt_pk_bf16_f32 v200, v200, v201
	v_cvt_pk_bf16_f32 v201, v202, v203
	v_mfma_f32_16x16x32_bf16 v[82:85], v[224:227], v[126:129], v[82:85]
	ds_read_b64_tr_b16 v[224:225], v244 offset:32768
	ds_read_b64_tr_b16 v[226:227], v244 offset:36864
	v_cvt_pk_bf16_f32 v202, v204, v205
	v_mfma_f32_16x16x32_bf16 v[70:73], v[228:231], v[110:113], v[70:73]
	v_cvt_pk_bf16_f32 v203, v206, v207
	v_cvt_pk_bf16_f32 v208, v208, v209
	v_mfma_f32_16x16x32_bf16 v[86:89], v[228:231], v[126:129], v[86:89]
	v_cvt_pk_bf16_f32 v209, v210, v211
	s_waitcnt lgkmcnt(10)
	v_mfma_f32_16x16x32_bf16 v[74:77], v[232:235], v[110:113], v[74:77]
	v_cvt_pk_bf16_f32 v210, v212, v213
	v_cvt_pk_bf16_f32 v211, v214, v215
	v_mfma_f32_16x16x32_bf16 v[90:93], v[232:235], v[126:129], v[90:93]
	v_cvt_pk_bf16_f32 v216, v216, v217
	v_mfma_f32_16x16x32_bf16 v[78:81], v[236:239], v[110:113], v[78:81]
	v_cvt_pk_bf16_f32 v217, v218, v219
	v_cvt_pk_bf16_f32 v218, v220, v221
	v_mfma_f32_16x16x32_bf16 v[94:97], v[236:239], v[126:129], v[94:97]
	v_cvt_pk_bf16_f32 v219, v222, v223
	s_waitcnt lgkmcnt(6)
	v_mfma_f32_16x16x32_bf16 v[2:5], v[192:195], v[166:169], v[2:5]
	v_mfma_f32_16x16x32_bf16 v[34:37], v[208:211], v[166:169], v[34:37]
	ds_read_b64_tr_b16 v[228:229], v245 offset:32768
	ds_read_b64_tr_b16 v[230:231], v245 offset:36864
	v_mfma_f32_16x16x32_bf16 v[6:9], v[192:195], v[170:173], v[6:9]
	v_mfma_f32_16x16x32_bf16 v[38:41], v[208:211], v[170:173], v[38:41]
	ds_read_b64_tr_b16 v[232:233], v246 offset:32768
	ds_read_b64_tr_b16 v[234:235], v246 offset:36864
	s_waitcnt lgkmcnt(6)
	v_mfma_f32_16x16x32_bf16 v[10:13], v[192:195], v[174:177], v[10:13]
	v_exp_f32_e32 v66, v66
	v_exp_f32_e32 v67, v67
	v_mfma_f32_16x16x32_bf16 v[42:45], v[208:211], v[174:177], v[42:45]
	ds_read_b64_tr_b16 v[236:237], v247 offset:32768
	ds_read_b64_tr_b16 v[238:239], v247 offset:36864
	v_exp_f32_e32 v68, v68
	v_mfma_f32_16x16x32_bf16 v[14:17], v[192:195], v[178:181], v[14:17]
	v_exp_f32_e32 v69, v69
	v_mfma_f32_16x16x32_bf16 v[46:49], v[208:211], v[178:181], v[46:49]
	ds_read_b64_tr_b16 v[166:167], v240 offset:40960
	ds_read_b64_tr_b16 v[168:169], v240 offset:45056
	v_exp_f32_e32 v82, v82
	s_waitcnt lgkmcnt(6)
	v_mfma_f32_16x16x32_bf16 v[18:21], v[192:195], v[224:227], v[18:21]
	v_exp_f32_e32 v83, v83
	v_mfma_f32_16x16x32_bf16 v[50:53], v[208:211], v[224:227], v[50:53]
	ds_read_b64_tr_b16 v[170:171], v241 offset:40960
	ds_read_b64_tr_b16 v[172:173], v241 offset:45056
	v_exp_f32_e32 v84, v84
	v_mfma_f32_16x16x32_bf16 v[22:25], v[192:195], v[228:231], v[22:25]
	v_exp_f32_e32 v85, v85
	v_exp_f32_e32 v70, v70
	v_mfma_f32_16x16x32_bf16 v[54:57], v[208:211], v[228:231], v[54:57]
	ds_read_b64_tr_b16 v[174:175], v242 offset:40960
	ds_read_b64_tr_b16 v[176:177], v242 offset:45056
	v_exp_f32_e32 v71, v71
	s_waitcnt lgkmcnt(6)
	v_mfma_f32_16x16x32_bf16 v[26:29], v[192:195], v[232:235], v[26:29]
	v_exp_f32_e32 v72, v72
	v_mfma_f32_16x16x32_bf16 v[58:61], v[208:211], v[232:235], v[58:61]
	ds_read_b64_tr_b16 v[178:179], v243 offset:40960
	ds_read_b64_tr_b16 v[180:181], v243 offset:45056
	v_exp_f32_e32 v73, v73
	v_mfma_f32_16x16x32_bf16 v[30:33], v[192:195], v[236:239], v[30:33]
	v_exp_f32_e32 v86, v86
	v_mfma_f32_16x16x32_bf16 v[62:65], v[208:211], v[236:239], v[62:65]
	ds_read_b64_tr_b16 v[224:225], v244 offset:40960
	ds_read_b64_tr_b16 v[226:227], v244 offset:45056
	v_exp_f32_e32 v87, v87
	s_waitcnt lgkmcnt(6)
	v_mfma_f32_16x16x32_bf16 v[2:5], v[200:203], v[166:169], v[2:5]
	v_exp_f32_e32 v88, v88
	v_mfma_f32_16x16x32_bf16 v[34:37], v[216:219], v[166:169], v[34:37]
	ds_read_b64_tr_b16 v[228:229], v245 offset:40960
	ds_read_b64_tr_b16 v[230:231], v245 offset:45056
	ds_read_b128 v[166:169], v187 offset:49152
	v_exp_f32_e32 v89, v89
	v_mfma_f32_16x16x32_bf16 v[6:9], v[200:203], v[170:173], v[6:9]
	v_exp_f32_e32 v74, v74
	v_exp_f32_e32 v75, v75
	v_mfma_f32_16x16x32_bf16 v[38:41], v[216:219], v[170:173], v[38:41]
	ds_read_b64_tr_b16 v[232:233], v246 offset:40960
	ds_read_b64_tr_b16 v[234:235], v246 offset:45056
	ds_read_b128 v[170:173], v187 offset:53248
	v_exp_f32_e32 v76, v76
	s_waitcnt lgkmcnt(8)
	v_mfma_f32_16x16x32_bf16 v[10:13], v[200:203], v[174:177], v[10:13]
	v_exp_f32_e32 v77, v77
	v_mfma_f32_16x16x32_bf16 v[42:45], v[216:219], v[174:177], v[42:45]
	ds_read_b64_tr_b16 v[236:237], v247 offset:40960
	ds_read_b64_tr_b16 v[238:239], v247 offset:45056
	ds_read_b128 v[174:177], v187 offset:57344
	v_exp_f32_e32 v90, v90
	v_mfma_f32_16x16x32_bf16 v[14:17], v[200:203], v[178:181], v[14:17]
	v_exp_f32_e32 v91, v91
	v_mfma_f32_16x16x32_bf16 v[46:49], v[216:219], v[178:181], v[46:49]
	ds_read_b128 v[178:181], v187 offset:61440
	v_exp_f32_e32 v92, v92
	s_waitcnt lgkmcnt(8)
	v_mfma_f32_16x16x32_bf16 v[18:21], v[200:203], v[224:227], v[18:21]
	v_exp_f32_e32 v93, v93
	v_exp_f32_e32 v78, v78
	v_mfma_f32_16x16x32_bf16 v[50:53], v[216:219], v[224:227], v[50:53]
	ds_read_b128 v[224:227], v188 offset:49152
	v_exp_f32_e32 v79, v79
	v_mfma_f32_16x16x32_bf16 v[22:25], v[200:203], v[228:231], v[22:25]
	v_exp_f32_e32 v80, v80
	v_mfma_f32_16x16x32_bf16 v[54:57], v[216:219], v[228:231], v[54:57]
	ds_read_b128 v[228:231], v188 offset:53248
	v_exp_f32_e32 v81, v81
	s_waitcnt lgkmcnt(4)
	v_mfma_f32_16x16x32_bf16 v[26:29], v[200:203], v[232:235], v[26:29]
	v_exp_f32_e32 v94, v94
	v_mfma_f32_16x16x32_bf16 v[58:61], v[216:219], v[232:235], v[58:61]
	ds_read_b128 v[232:235], v188 offset:57344
	v_exp_f32_e32 v95, v95
	v_mfma_f32_16x16x32_bf16 v[30:33], v[200:203], v[236:239], v[30:33]
	v_exp_f32_e32 v96, v96
	v_mfma_f32_16x16x32_bf16 v[62:65], v[216:219], v[236:239], v[62:65]
	ds_read_b128 v[236:239], v188 offset:61440
	v_exp_f32_e32 v97, v97
	s_barrier
	v_mfma_f32_16x16x32_bf16 v[192:195], v[166:169], v[98:101], 0
	v_add_f32_e32 v130, v66, v67
	v_add_f32_e32 v131, v68, v69
	v_mfma_f32_16x16x32_bf16 v[208:211], v[166:169], v[114:117], 0
	ds_read_b128 v[166:169], v189 offset:49152
	s_add_i32 m0, s45, 0x0
	v_add_f32_e32 v130, v70, v130
	global_load_lds_dwordx4 v152, s[64:65]
	v_mfma_f32_16x16x32_bf16 v[196:199], v[170:173], v[98:101], 0
	v_add_f32_e32 v131, v71, v131
	v_add_f32_e32 v130, v72, v130
	v_mfma_f32_16x16x32_bf16 v[212:215], v[170:173], v[114:117], 0
	ds_read_b128 v[170:173], v189 offset:53248
	s_add_i32 m0, s45, 0x4000
	v_add_f32_e32 v131, v73, v131
	global_load_lds_dwordx4 v150, s[62:63]
	s_waitcnt lgkmcnt(6)
	v_mfma_f32_16x16x32_bf16 v[200:203], v[174:177], v[98:101], 0
	v_add_f32_e32 v130, v74, v130
	v_add_f32_e32 v131, v75, v131
	v_mfma_f32_16x16x32_bf16 v[216:219], v[174:177], v[114:117], 0
	ds_read_b128 v[174:177], v189 offset:57344
	s_add_i32 m0, s45, 0x2000
	v_add_f32_e32 v130, v76, v130
	global_load_lds_dwordx4 v153, s[64:65]
	v_mfma_f32_16x16x32_bf16 v[204:207], v[178:181], v[98:101], 0
	v_add_f32_e32 v131, v77, v131
	v_add_f32_e32 v130, v78, v130
	v_mfma_f32_16x16x32_bf16 v[220:223], v[178:181], v[114:117], 0
	ds_read_b128 v[178:181], v189 offset:61440
	s_add_i32 m0, s45, 0x6000
	v_add_f32_e32 v131, v79, v131
	global_load_lds_dwordx4 v151, s[62:63]
	s_add_u32 s62, s62, 0x4000
	s_addc_u32 s63, s63, 0
	s_add_u32 s64, s64, 0x4000
	s_addc_u32 s65, s65, 0
	s_waitcnt lgkmcnt(6)
	v_mfma_f32_16x16x32_bf16 v[192:195], v[224:227], v[102:105], v[192:195]
	v_add_f32_e32 v130, v80, v130
	v_add_f32_e32 v131, v81, v131
	v_mfma_f32_16x16x32_bf16 v[208:211], v[224:227], v[118:121], v[208:211]
	ds_read_b128 v[224:227], v190 offset:49152
	v_add_f32_e32 v130, v130, v131
	v_mfma_f32_16x16x32_bf16 v[196:199], v[228:231], v[102:105], v[196:199]
	v_add_f32_e32 v165, v165, v130
	v_add_f32_e32 v132, v82, v83
	v_mfma_f32_16x16x32_bf16 v[212:215], v[228:231], v[118:121], v[212:215]
	ds_read_b128 v[228:231], v190 offset:53248
	v_add_f32_e32 v133, v84, v85
	s_waitcnt lgkmcnt(6)
	v_mfma_f32_16x16x32_bf16 v[200:203], v[232:235], v[102:105], v[200:203]
	v_add_f32_e32 v132, v86, v132
	v_add_f32_e32 v133, v87, v133
	v_mfma_f32_16x16x32_bf16 v[216:219], v[232:235], v[118:121], v[216:219]
	ds_read_b128 v[232:235], v190 offset:57344
	v_add_f32_e32 v132, v88, v132
	v_mfma_f32_16x16x32_bf16 v[204:207], v[236:239], v[102:105], v[204:207]
	v_add_f32_e32 v133, v89, v133
	v_add_f32_e32 v132, v90, v132
	v_mfma_f32_16x16x32_bf16 v[220:223], v[236:239], v[118:121], v[220:223]
	ds_read_b128 v[236:239], v190 offset:61440
	v_add_f32_e32 v133, v91, v133
	s_waitcnt lgkmcnt(6)
	v_mfma_f32_16x16x32_bf16 v[192:195], v[166:169], v[106:109], v[192:195]
	v_add_f32_e32 v132, v92, v132
	v_add_f32_e32 v133, v93, v133
	v_mfma_f32_16x16x32_bf16 v[208:211], v[166:169], v[122:125], v[208:211]
	ds_read_b64_tr_b16 v[166:167], v142 offset:0
	ds_read_b64_tr_b16 v[168:169], v142 offset:4096
	v_add_f32_e32 v132, v94, v132
	v_mfma_f32_16x16x32_bf16 v[196:199], v[170:173], v[106:109], v[196:199]
	v_add_f32_e32 v133, v95, v133
	v_add_f32_e32 v132, v96, v132
	v_mfma_f32_16x16x32_bf16 v[212:215], v[170:173], v[122:125], v[212:215]
	ds_read_b64_tr_b16 v[170:171], v143 offset:0
	ds_read_b64_tr_b16 v[172:173], v143 offset:4096
	v_add_f32_e32 v133, v97, v133
	s_waitcnt lgkmcnt(8)
	v_mfma_f32_16x16x32_bf16 v[200:203], v[174:177], v[106:109], v[200:203]
	v_add_f32_e32 v132, v132, v133
	v_add_f32_e32 v163, v163, v132
	v_mfma_f32_16x16x32_bf16 v[216:219], v[174:177], v[122:125], v[216:219]
	ds_read_b64_tr_b16 v[174:175], v144 offset:0
	ds_read_b64_tr_b16 v[176:177], v144 offset:4096
	v_cvt_pk_bf16_f32 v66, v66, v67
	v_mfma_f32_16x16x32_bf16 v[204:207], v[178:181], v[106:109], v[204:207]
	v_cvt_pk_bf16_f32 v67, v68, v69
	v_cvt_pk_bf16_f32 v68, v70, v71
	v_mfma_f32_16x16x32_bf16 v[220:223], v[178:181], v[122:125], v[220:223]
	ds_read_b64_tr_b16 v[178:179], v145 offset:0
	ds_read_b64_tr_b16 v[180:181], v145 offset:4096
	v_cvt_pk_bf16_f32 v69, v72, v73
	s_waitcnt lgkmcnt(10)
	v_mfma_f32_16x16x32_bf16 v[192:195], v[224:227], v[110:113], v[192:195]
	v_cvt_pk_bf16_f32 v74, v74, v75
	v_cvt_pk_bf16_f32 v75, v76, v77
	v_mfma_f32_16x16x32_bf16 v[208:211], v[224:227], v[126:129], v[208:211]
	ds_read_b64_tr_b16 v[224:225], v146 offset:0
	ds_read_b64_tr_b16 v[226:227], v146 offset:4096
	v_cvt_pk_bf16_f32 v76, v78, v79
	v_mfma_f32_16x16x32_bf16 v[196:199], v[228:231], v[110:113], v[196:199]
	v_cvt_pk_bf16_f32 v77, v80, v81
	v_cvt_pk_bf16_f32 v82, v82, v83
	v_mfma_f32_16x16x32_bf16 v[212:215], v[228:231], v[126:129], v[212:215]
	v_cvt_pk_bf16_f32 v83, v84, v85
	s_waitcnt lgkmcnt(10)
	v_mfma_f32_16x16x32_bf16 v[200:203], v[232:235], v[110:113], v[200:203]
	v_cvt_pk_bf16_f32 v84, v86, v87
	v_cvt_pk_bf16_f32 v85, v88, v89
	v_mfma_f32_16x16x32_bf16 v[216:219], v[232:235], v[126:129], v[216:219]
	v_cvt_pk_bf16_f32 v90, v90, v91
	v_mfma_f32_16x16x32_bf16 v[204:207], v[236:239], v[110:113], v[204:207]
	v_cvt_pk_bf16_f32 v91, v92, v93
	v_cvt_pk_bf16_f32 v92, v94, v95
	v_mfma_f32_16x16x32_bf16 v[220:223], v[236:239], v[126:129], v[220:223]
	v_cvt_pk_bf16_f32 v93, v96, v97
	s_waitcnt lgkmcnt(6)
	v_mfma_f32_16x16x32_bf16 v[2:5], v[66:69], v[166:169], v[2:5]
	v_mfma_f32_16x16x32_bf16 v[34:37], v[82:85], v[166:169], v[34:37]
	ds_read_b64_tr_b16 v[228:229], v147 offset:0
	ds_read_b64_tr_b16 v[230:231], v147 offset:4096
	v_mfma_f32_16x16x32_bf16 v[6:9], v[66:69], v[170:173], v[6:9]
	v_mfma_f32_16x16x32_bf16 v[38:41], v[82:85], v[170:173], v[38:41]
	ds_read_b64_tr_b16 v[232:233], v148 offset:0
	ds_read_b64_tr_b16 v[234:235], v148 offset:4096
	s_waitcnt lgkmcnt(6)
	v_mfma_f32_16x16x32_bf16 v[10:13], v[66:69], v[174:177], v[10:13]
	v_exp_f32_e32 v192, v192
	v_exp_f32_e32 v193, v193
	v_mfma_f32_16x16x32_bf16 v[42:45], v[82:85], v[174:177], v[42:45]
	ds_read_b64_tr_b16 v[236:237], v149 offset:0
	ds_read_b64_tr_b16 v[238:239], v149 offset:4096
	v_exp_f32_e32 v194, v194
	v_mfma_f32_16x16x32_bf16 v[14:17], v[66:69], v[178:181], v[14:17]
	v_exp_f32_e32 v195, v195
	v_mfma_f32_16x16x32_bf16 v[46:49], v[82:85], v[178:181], v[46:49]
	ds_read_b64_tr_b16 v[166:167], v142 offset:8192
	ds_read_b64_tr_b16 v[168:169], v142 offset:12288
	v_exp_f32_e32 v208, v208
	s_waitcnt lgkmcnt(6)
	v_mfma_f32_16x16x32_bf16 v[18:21], v[66:69], v[224:227], v[18:21]
	v_exp_f32_e32 v209, v209
	v_mfma_f32_16x16x32_bf16 v[50:53], v[82:85], v[224:227], v[50:53]
	ds_read_b64_tr_b16 v[170:171], v143 offset:8192
	ds_read_b64_tr_b16 v[172:173], v143 offset:12288
	v_exp_f32_e32 v210, v210
	v_mfma_f32_16x16x32_bf16 v[22:25], v[66:69], v[228:231], v[22:25]
	v_exp_f32_e32 v211, v211
	v_exp_f32_e32 v196, v196
	v_mfma_f32_16x16x32_bf16 v[54:57], v[82:85], v[228:231], v[54:57]
	ds_read_b64_tr_b16 v[174:175], v144 offset:8192
	ds_read_b64_tr_b16 v[176:177], v144 offset:12288
	v_exp_f32_e32 v197, v197
	s_waitcnt lgkmcnt(6)
	v_mfma_f32_16x16x32_bf16 v[26:29], v[66:69], v[232:235], v[26:29]
	v_exp_f32_e32 v198, v198
	v_mfma_f32_16x16x32_bf16 v[58:61], v[82:85], v[232:235], v[58:61]
	ds_read_b64_tr_b16 v[178:179], v145 offset:8192
	ds_read_b64_tr_b16 v[180:181], v145 offset:12288
	v_exp_f32_e32 v199, v199
	v_mfma_f32_16x16x32_bf16 v[30:33], v[66:69], v[236:239], v[30:33]
	v_exp_f32_e32 v212, v212
	v_mfma_f32_16x16x32_bf16 v[62:65], v[82:85], v[236:239], v[62:65]
	ds_read_b64_tr_b16 v[224:225], v146 offset:8192
	ds_read_b64_tr_b16 v[226:227], v146 offset:12288
	v_exp_f32_e32 v213, v213
	s_waitcnt lgkmcnt(6)
	v_mfma_f32_16x16x32_bf16 v[2:5], v[74:77], v[166:169], v[2:5]
	v_exp_f32_e32 v214, v214
	v_mfma_f32_16x16x32_bf16 v[34:37], v[90:93], v[166:169], v[34:37]
	ds_read_b64_tr_b16 v[228:229], v147 offset:8192
	ds_read_b64_tr_b16 v[230:231], v147 offset:12288
	v_exp_f32_e32 v215, v215
	v_mfma_f32_16x16x32_bf16 v[6:9], v[74:77], v[170:173], v[6:9]
	v_exp_f32_e32 v200, v200
	v_exp_f32_e32 v201, v201
	v_mfma_f32_16x16x32_bf16 v[38:41], v[90:93], v[170:173], v[38:41]
	ds_read_b64_tr_b16 v[232:233], v148 offset:8192
	ds_read_b64_tr_b16 v[234:235], v148 offset:12288
	v_exp_f32_e32 v202, v202
	s_waitcnt lgkmcnt(6)
	v_mfma_f32_16x16x32_bf16 v[10:13], v[74:77], v[174:177], v[10:13]
	v_exp_f32_e32 v203, v203
	v_mfma_f32_16x16x32_bf16 v[42:45], v[90:93], v[174:177], v[42:45]
	ds_read_b64_tr_b16 v[236:237], v149 offset:8192
	ds_read_b64_tr_b16 v[238:239], v149 offset:12288
	v_exp_f32_e32 v216, v216
	v_mfma_f32_16x16x32_bf16 v[14:17], v[74:77], v[178:181], v[14:17]
	v_exp_f32_e32 v217, v217
	v_mfma_f32_16x16x32_bf16 v[46:49], v[90:93], v[178:181], v[46:49]
	v_exp_f32_e32 v218, v218
	s_waitcnt lgkmcnt(4)
	v_mfma_f32_16x16x32_bf16 v[18:21], v[74:77], v[224:227], v[18:21]
	v_exp_f32_e32 v219, v219
	v_exp_f32_e32 v204, v204
	v_mfma_f32_16x16x32_bf16 v[50:53], v[90:93], v[224:227], v[50:53]
	v_exp_f32_e32 v205, v205
	v_mfma_f32_16x16x32_bf16 v[22:25], v[74:77], v[228:231], v[22:25]
	v_exp_f32_e32 v206, v206
	v_mfma_f32_16x16x32_bf16 v[54:57], v[90:93], v[228:231], v[54:57]
	v_exp_f32_e32 v207, v207
	s_waitcnt lgkmcnt(0)
	v_mfma_f32_16x16x32_bf16 v[26:29], v[74:77], v[232:235], v[26:29]
	v_exp_f32_e32 v220, v220
	v_mfma_f32_16x16x32_bf16 v[58:61], v[90:93], v[232:235], v[58:61]
	v_exp_f32_e32 v221, v221
	v_mfma_f32_16x16x32_bf16 v[30:33], v[74:77], v[236:239], v[30:33]
	v_exp_f32_e32 v222, v222
	v_mfma_f32_16x16x32_bf16 v[62:65], v[90:93], v[236:239], v[62:65]
	v_exp_f32_e32 v223, v223
	s_add_i32 m0, s45, 0x8000
	s_nop 0
	global_load_lds_dwordx4 v152, s[64:65]
	s_add_i32 m0, s45, 0xc000
	s_nop 0
	global_load_lds_dwordx4 v150, s[62:63]
	s_add_i32 m0, s45, 0xa000
	s_nop 0
	global_load_lds_dwordx4 v153, s[64:65]
	s_add_i32 m0, s45, 0xe000
	s_nop 0
	global_load_lds_dwordx4 v151, s[62:63]
	s_add_u32 s62, s62, 0x4000
	s_addc_u32 s63, s63, 0
	s_add_u32 s64, s64, 0x4000
	s_addc_u32 s65, s65, 0
	global_load_dwordx4 v[98:101], v154, s[60:61]
	global_load_dwordx4 v[102:105], v154, s[60:61] offset:64
	global_load_dwordx4 v[106:109], v154, s[60:61] offset:128
	global_load_dwordx4 v[110:113], v154, s[60:61] offset:192
	global_load_dwordx4 v[114:117], v155, s[60:61]
	global_load_dwordx4 v[118:121], v155, s[60:61] offset:64
	global_load_dwordx4 v[122:125], v155, s[60:61] offset:128
	global_load_dwordx4 v[126:129], v155, s[60:61] offset:192
	s_barrier
	ds_read_b64_tr_b16 v[166:167], v142 offset:32768
	ds_read_b64_tr_b16 v[168:169], v142 offset:36864
	ds_read_b64_tr_b16 v[170:171], v143 offset:32768
	ds_read_b64_tr_b16 v[172:173], v143 offset:36864
	ds_read_b64_tr_b16 v[174:175], v144 offset:32768
	ds_read_b64_tr_b16 v[176:177], v144 offset:36864
	ds_read_b64_tr_b16 v[178:179], v145 offset:32768
	ds_read_b64_tr_b16 v[180:181], v145 offset:36864
	ds_read_b64_tr_b16 v[224:225], v146 offset:32768
	ds_read_b64_tr_b16 v[226:227], v146 offset:36864
	v_add_f32_e32 v130, v192, v193
	v_add_f32_e32 v131, v194, v195
	v_add_f32_e32 v130, v196, v130
	v_add_f32_e32 v131, v197, v131
	v_add_f32_e32 v130, v198, v130
	v_add_f32_e32 v131, v199, v131
	v_add_f32_e32 v130, v200, v130
	v_add_f32_e32 v131, v201, v131
	v_add_f32_e32 v130, v202, v130
	v_add_f32_e32 v131, v203, v131
	v_add_f32_e32 v130, v204, v130
	v_add_f32_e32 v131, v205, v131
	v_add_f32_e32 v130, v206, v130
	v_add_f32_e32 v131, v207, v131
	v_add_f32_e32 v130, v130, v131
	v_add_f32_e32 v165, v165, v130
	v_add_f32_e32 v132, v208, v209
	v_add_f32_e32 v133, v210, v211
	v_add_f32_e32 v132, v212, v132
	v_add_f32_e32 v133, v213, v133
	v_add_f32_e32 v132, v214, v132
	v_add_f32_e32 v133, v215, v133
	v_add_f32_e32 v132, v216, v132
	v_add_f32_e32 v133, v217, v133
	v_add_f32_e32 v132, v218, v132
	v_add_f32_e32 v133, v219, v133
	v_add_f32_e32 v132, v220, v132
	v_add_f32_e32 v133, v221, v133
	v_add_f32_e32 v132, v222, v132
	v_add_f32_e32 v133, v223, v133
	v_add_f32_e32 v132, v132, v133
	v_add_f32_e32 v163, v163, v132
	v_cvt_pk_bf16_f32 v192, v192, v193
	v_cvt_pk_bf16_f32 v193, v194, v195
	v_cvt_pk_bf16_f32 v194, v196, v197
	v_cvt_pk_bf16_f32 v195, v198, v199
	v_cvt_pk_bf16_f32 v200, v200, v201
	v_cvt_pk_bf16_f32 v201, v202, v203
	v_cvt_pk_bf16_f32 v202, v204, v205
	v_cvt_pk_bf16_f32 v203, v206, v207
	v_cvt_pk_bf16_f32 v208, v208, v209
	v_cvt_pk_bf16_f32 v209, v210, v211
	v_cvt_pk_bf16_f32 v210, v212, v213
	v_cvt_pk_bf16_f32 v211, v214, v215
	v_cvt_pk_bf16_f32 v216, v216, v217
	v_cvt_pk_bf16_f32 v217, v218, v219
	v_cvt_pk_bf16_f32 v218, v220, v221
	v_cvt_pk_bf16_f32 v219, v222, v223
	s_waitcnt lgkmcnt(6)
	v_mfma_f32_16x16x32_bf16 v[2:5], v[192:195], v[166:169], v[2:5]
	v_mfma_f32_16x16x32_bf16 v[34:37], v[208:211], v[166:169], v[34:37]
	ds_read_b64_tr_b16 v[228:229], v147 offset:32768
	ds_read_b64_tr_b16 v[230:231], v147 offset:36864
	v_mfma_f32_16x16x32_bf16 v[6:9], v[192:195], v[170:173], v[6:9]
	v_mfma_f32_16x16x32_bf16 v[38:41], v[208:211], v[170:173], v[38:41]
	ds_read_b64_tr_b16 v[232:233], v148 offset:32768
	ds_read_b64_tr_b16 v[234:235], v148 offset:36864
	s_waitcnt lgkmcnt(6)
	v_mfma_f32_16x16x32_bf16 v[10:13], v[192:195], v[174:177], v[10:13]
	v_mfma_f32_16x16x32_bf16 v[42:45], v[208:211], v[174:177], v[42:45]
	ds_read_b64_tr_b16 v[236:237], v149 offset:32768
	ds_read_b64_tr_b16 v[238:239], v149 offset:36864
	v_mfma_f32_16x16x32_bf16 v[14:17], v[192:195], v[178:181], v[14:17]
	v_mfma_f32_16x16x32_bf16 v[46:49], v[208:211], v[178:181], v[46:49]
	ds_read_b64_tr_b16 v[166:167], v142 offset:40960
	ds_read_b64_tr_b16 v[168:169], v142 offset:45056
	s_waitcnt lgkmcnt(6)
	v_mfma_f32_16x16x32_bf16 v[18:21], v[192:195], v[224:227], v[18:21]
	v_mfma_f32_16x16x32_bf16 v[50:53], v[208:211], v[224:227], v[50:53]
	ds_read_b64_tr_b16 v[170:171], v143 offset:40960
	ds_read_b64_tr_b16 v[172:173], v143 offset:45056
	v_mfma_f32_16x16x32_bf16 v[22:25], v[192:195], v[228:231], v[22:25]
	v_mfma_f32_16x16x32_bf16 v[54:57], v[208:211], v[228:231], v[54:57]
	ds_read_b64_tr_b16 v[174:175], v144 offset:40960
	ds_read_b64_tr_b16 v[176:177], v144 offset:45056
	s_waitcnt lgkmcnt(6)
	v_mfma_f32_16x16x32_bf16 v[26:29], v[192:195], v[232:235], v[26:29]
	v_mfma_f32_16x16x32_bf16 v[58:61], v[208:211], v[232:235], v[58:61]
	ds_read_b64_tr_b16 v[178:179], v145 offset:40960
	ds_read_b64_tr_b16 v[180:181], v145 offset:45056
	v_mfma_f32_16x16x32_bf16 v[30:33], v[192:195], v[236:239], v[30:33]
	v_mfma_f32_16x16x32_bf16 v[62:65], v[208:211], v[236:239], v[62:65]
	ds_read_b64_tr_b16 v[224:225], v146 offset:40960
	ds_read_b64_tr_b16 v[226:227], v146 offset:45056
	s_waitcnt lgkmcnt(6)
	v_mfma_f32_16x16x32_bf16 v[2:5], v[200:203], v[166:169], v[2:5]
	v_mfma_f32_16x16x32_bf16 v[34:37], v[216:219], v[166:169], v[34:37]
	ds_read_b64_tr_b16 v[228:229], v147 offset:40960
	ds_read_b64_tr_b16 v[230:231], v147 offset:45056
	v_mfma_f32_16x16x32_bf16 v[6:9], v[200:203], v[170:173], v[6:9]
	v_mfma_f32_16x16x32_bf16 v[38:41], v[216:219], v[170:173], v[38:41]
	ds_read_b64_tr_b16 v[232:233], v148 offset:40960
	ds_read_b64_tr_b16 v[234:235], v148 offset:45056
	s_waitcnt lgkmcnt(6)
	v_mfma_f32_16x16x32_bf16 v[10:13], v[200:203], v[174:177], v[10:13]
	v_mfma_f32_16x16x32_bf16 v[42:45], v[216:219], v[174:177], v[42:45]
	ds_read_b64_tr_b16 v[236:237], v149 offset:40960
	ds_read_b64_tr_b16 v[238:239], v149 offset:45056
	v_mfma_f32_16x16x32_bf16 v[14:17], v[200:203], v[178:181], v[14:17]
	v_mfma_f32_16x16x32_bf16 v[46:49], v[216:219], v[178:181], v[46:49]
	s_waitcnt lgkmcnt(4)
	v_mfma_f32_16x16x32_bf16 v[18:21], v[200:203], v[224:227], v[18:21]
	v_mfma_f32_16x16x32_bf16 v[50:53], v[216:219], v[224:227], v[50:53]
	v_mfma_f32_16x16x32_bf16 v[22:25], v[200:203], v[228:231], v[22:25]
	v_mfma_f32_16x16x32_bf16 v[54:57], v[216:219], v[228:231], v[54:57]
	s_waitcnt lgkmcnt(0)
	v_mfma_f32_16x16x32_bf16 v[26:29], v[200:203], v[232:235], v[26:29]
	v_mfma_f32_16x16x32_bf16 v[58:61], v[216:219], v[232:235], v[58:61]
	v_mfma_f32_16x16x32_bf16 v[30:33], v[200:203], v[236:239], v[30:33]
	v_mfma_f32_16x16x32_bf16 v[62:65], v[216:219], v[236:239], v[62:65]
	ds_write_b32 v160, v165
	ds_write_b32 v160, v163 offset:256
	s_waitcnt lgkmcnt(0)
	ds_read_b128 v[66:69], v161 offset:0
	ds_read_b128 v[70:73], v161 offset:64
	ds_read_b128 v[74:77], v161 offset:128
	ds_read_b128 v[78:81], v161 offset:192
	ds_read_b128 v[82:85], v161 offset:256
	ds_read_b128 v[86:89], v161 offset:320
	ds_read_b128 v[90:93], v161 offset:384
	ds_read_b128 v[94:97], v161 offset:448
	s_waitcnt lgkmcnt(0)
	v_add_f32_e32 v66, v66, v70
	v_add_f32_e32 v74, v74, v78
	v_add_f32_e32 v66, v66, v74
	v_rcp_f32_e32 v192, v66
	v_add_f32_e32 v67, v67, v71
	v_add_f32_e32 v75, v75, v79
	v_add_f32_e32 v67, v67, v75
	v_rcp_f32_e32 v193, v67
	v_add_f32_e32 v68, v68, v72
	v_add_f32_e32 v76, v76, v80
	v_add_f32_e32 v68, v68, v76
	v_rcp_f32_e32 v194, v68
	v_add_f32_e32 v69, v69, v73
	v_add_f32_e32 v77, v77, v81
	v_add_f32_e32 v69, v69, v77
	v_rcp_f32_e32 v195, v69
	v_add_f32_e32 v82, v82, v86
	v_add_f32_e32 v90, v90, v94
	v_add_f32_e32 v82, v82, v90
	v_rcp_f32_e32 v196, v82
	v_add_f32_e32 v83, v83, v87
	v_add_f32_e32 v91, v91, v95
	v_add_f32_e32 v83, v83, v91
	v_rcp_f32_e32 v197, v83
	v_add_f32_e32 v84, v84, v88
	v_add_f32_e32 v92, v92, v96
	v_add_f32_e32 v84, v84, v92
	v_rcp_f32_e32 v198, v84
	v_add_f32_e32 v85, v85, v89
	v_add_f32_e32 v93, v93, v97
	v_add_f32_e32 v85, v85, v93
	v_rcp_f32_e32 v199, v85
	s_nop 0
	v_mul_f32_e32 v2, v2, v192
	v_mul_f32_e32 v6, v6, v192
	v_cvt_pk_bf16_f32 v200, v2, v6
	global_store_short v156, v200, s[46:47] offset:0
	global_store_short_d16_hi v156, v200, s[46:47] offset:32
	v_mul_f32_e32 v10, v10, v192
	v_mul_f32_e32 v14, v14, v192
	v_cvt_pk_bf16_f32 v201, v10, v14
	global_store_short v156, v201, s[46:47] offset:64
	global_store_short_d16_hi v156, v201, s[46:47] offset:96
	v_mul_f32_e32 v18, v18, v192
	v_mul_f32_e32 v22, v22, v192
	v_cvt_pk_bf16_f32 v202, v18, v22
	global_store_short v156, v202, s[46:47] offset:128
	global_store_short_d16_hi v156, v202, s[46:47] offset:160
	v_mul_f32_e32 v26, v26, v192
	v_mul_f32_e32 v30, v30, v192
	v_cvt_pk_bf16_f32 v203, v26, v30
	global_store_short v156, v203, s[46:47] offset:192
	global_store_short_d16_hi v156, v203, s[46:47] offset:224
	v_mul_f32_e32 v3, v3, v193
	v_mul_f32_e32 v7, v7, v193
	v_cvt_pk_bf16_f32 v204, v3, v7
	global_store_short v156, v204, s[46:47] offset:2048
	global_store_short_d16_hi v156, v204, s[46:47] offset:2080
	v_mul_f32_e32 v11, v11, v193
	v_mul_f32_e32 v15, v15, v193
	v_cvt_pk_bf16_f32 v205, v11, v15
	global_store_short v156, v205, s[46:47] offset:2112
	global_store_short_d16_hi v156, v205, s[46:47] offset:2144
	v_mul_f32_e32 v19, v19, v193
	v_mul_f32_e32 v23, v23, v193
	v_cvt_pk_bf16_f32 v206, v19, v23
	global_store_short v156, v206, s[46:47] offset:2176
	global_store_short_d16_hi v156, v206, s[46:47] offset:2208
	v_mul_f32_e32 v27, v27, v193
	v_mul_f32_e32 v31, v31, v193
	v_cvt_pk_bf16_f32 v207, v27, v31
	global_store_short v156, v207, s[46:47] offset:2240
	global_store_short_d16_hi v156, v207, s[46:47] offset:2272
	v_mul_f32_e32 v4, v4, v194
	v_mul_f32_e32 v8, v8, v194
	v_cvt_pk_bf16_f32 v200, v4, v8
	global_store_short v157, v200, s[46:47] offset:0
	global_store_short_d16_hi v157, v200, s[46:47] offset:32
	v_mul_f32_e32 v12, v12, v194
	v_mul_f32_e32 v16, v16, v194
	v_cvt_pk_bf16_f32 v201, v12, v16
	global_store_short v157, v201, s[46:47] offset:64
	global_store_short_d16_hi v157, v201, s[46:47] offset:96
	v_mul_f32_e32 v20, v20, v194
	v_mul_f32_e32 v24, v24, v194
	v_cvt_pk_bf16_f32 v202, v20, v24
	global_store_short v157, v202, s[46:47] offset:128
	global_store_short_d16_hi v157, v202, s[46:47] offset:160
	v_mul_f32_e32 v28, v28, v194
	v_mul_f32_e32 v32, v32, v194
	v_cvt_pk_bf16_f32 v203, v28, v32
	global_store_short v157, v203, s[46:47] offset:192
	global_store_short_d16_hi v157, v203, s[46:47] offset:224
	v_mul_f32_e32 v5, v5, v195
	v_mul_f32_e32 v9, v9, v195
	v_cvt_pk_bf16_f32 v204, v5, v9
	global_store_short v157, v204, s[46:47] offset:2048
	global_store_short_d16_hi v157, v204, s[46:47] offset:2080
	v_mul_f32_e32 v13, v13, v195
	v_mul_f32_e32 v17, v17, v195
	v_cvt_pk_bf16_f32 v205, v13, v17
	global_store_short v157, v205, s[46:47] offset:2112
	global_store_short_d16_hi v157, v205, s[46:47] offset:2144
	v_mul_f32_e32 v21, v21, v195
	v_mul_f32_e32 v25, v25, v195
	v_cvt_pk_bf16_f32 v206, v21, v25
	global_store_short v157, v206, s[46:47] offset:2176
	global_store_short_d16_hi v157, v206, s[46:47] offset:2208
	v_mul_f32_e32 v29, v29, v195
	v_mul_f32_e32 v33, v33, v195
	v_cvt_pk_bf16_f32 v207, v29, v33
	global_store_short v157, v207, s[46:47] offset:2240
	global_store_short_d16_hi v157, v207, s[46:47] offset:2272
	v_mul_f32_e32 v34, v34, v196
	v_mul_f32_e32 v38, v38, v196
	v_cvt_pk_bf16_f32 v200, v34, v38
	global_store_short v158, v200, s[46:47] offset:0
	global_store_short_d16_hi v158, v200, s[46:47] offset:32
	v_mul_f32_e32 v42, v42, v196
	v_mul_f32_e32 v46, v46, v196
	v_cvt_pk_bf16_f32 v201, v42, v46
	global_store_short v158, v201, s[46:47] offset:64
	global_store_short_d16_hi v158, v201, s[46:47] offset:96
	v_mul_f32_e32 v50, v50, v196
	v_mul_f32_e32 v54, v54, v196
	v_cvt_pk_bf16_f32 v202, v50, v54
	global_store_short v158, v202, s[46:47] offset:128
	global_store_short_d16_hi v158, v202, s[46:47] offset:160
	v_mul_f32_e32 v58, v58, v196
	v_mul_f32_e32 v62, v62, v196
	v_cvt_pk_bf16_f32 v203, v58, v62
	global_store_short v158, v203, s[46:47] offset:192
	global_store_short_d16_hi v158, v203, s[46:47] offset:224
	v_mul_f32_e32 v35, v35, v197
	v_mul_f32_e32 v39, v39, v197
	v_cvt_pk_bf16_f32 v204, v35, v39
	global_store_short v158, v204, s[46:47] offset:2048
	global_store_short_d16_hi v158, v204, s[46:47] offset:2080
	v_mul_f32_e32 v43, v43, v197
	v_mul_f32_e32 v47, v47, v197
	v_cvt_pk_bf16_f32 v205, v43, v47
	global_store_short v158, v205, s[46:47] offset:2112
	global_store_short_d16_hi v158, v205, s[46:47] offset:2144
	v_mul_f32_e32 v51, v51, v197
	v_mul_f32_e32 v55, v55, v197
	v_cvt_pk_bf16_f32 v206, v51, v55
	global_store_short v158, v206, s[46:47] offset:2176
	global_store_short_d16_hi v158, v206, s[46:47] offset:2208
	v_mul_f32_e32 v59, v59, v197
	v_mul_f32_e32 v63, v63, v197
	v_cvt_pk_bf16_f32 v207, v59, v63
	global_store_short v158, v207, s[46:47] offset:2240
	global_store_short_d16_hi v158, v207, s[46:47] offset:2272
	v_mul_f32_e32 v36, v36, v198
	v_mul_f32_e32 v40, v40, v198
	v_cvt_pk_bf16_f32 v200, v36, v40
	global_store_short v159, v200, s[46:47] offset:0
	global_store_short_d16_hi v159, v200, s[46:47] offset:32
	v_mul_f32_e32 v44, v44, v198
	v_mul_f32_e32 v48, v48, v198
	v_cvt_pk_bf16_f32 v201, v44, v48
	global_store_short v159, v201, s[46:47] offset:64
	global_store_short_d16_hi v159, v201, s[46:47] offset:96
	v_mul_f32_e32 v52, v52, v198
	v_mul_f32_e32 v56, v56, v198
	v_cvt_pk_bf16_f32 v202, v52, v56
	global_store_short v159, v202, s[46:47] offset:128
	global_store_short_d16_hi v159, v202, s[46:47] offset:160
	v_mul_f32_e32 v60, v60, v198
	v_mul_f32_e32 v64, v64, v198
	v_cvt_pk_bf16_f32 v203, v60, v64
	global_store_short v159, v203, s[46:47] offset:192
	global_store_short_d16_hi v159, v203, s[46:47] offset:224
	v_mul_f32_e32 v37, v37, v199
	v_mul_f32_e32 v41, v41, v199
	v_cvt_pk_bf16_f32 v204, v37, v41
	global_store_short v159, v204, s[46:47] offset:2048
	global_store_short_d16_hi v159, v204, s[46:47] offset:2080
	v_mul_f32_e32 v45, v45, v199
	v_mul_f32_e32 v49, v49, v199
	v_cvt_pk_bf16_f32 v205, v45, v49
	global_store_short v159, v205, s[46:47] offset:2112
	global_store_short_d16_hi v159, v205, s[46:47] offset:2144
	v_mul_f32_e32 v53, v53, v199
	v_mul_f32_e32 v57, v57, v199
	v_cvt_pk_bf16_f32 v206, v53, v57
	global_store_short v159, v206, s[46:47] offset:2176
	global_store_short_d16_hi v159, v206, s[46:47] offset:2208
	v_mul_f32_e32 v61, v61, v199
	v_mul_f32_e32 v65, v65, v199
	v_cvt_pk_bf16_f32 v207, v61, v65
	global_store_short v159, v207, s[46:47] offset:2240
	global_store_short_d16_hi v159, v207, s[46:47] offset:2272
	s_mov_b32 s46, s18
	s_mov_b32 s47, s19
	v_mov_b32_e32 v2, 0
	v_mov_b32_e32 v3, 0
	v_mov_b32_e32 v4, 0
	v_mov_b32_e32 v5, 0
	v_mov_b32_e32 v6, 0
	v_mov_b32_e32 v7, 0
	v_mov_b32_e32 v8, 0
	v_mov_b32_e32 v9, 0
	v_mov_b32_e32 v10, 0
	v_mov_b32_e32 v11, 0
	v_mov_b32_e32 v12, 0
	v_mov_b32_e32 v13, 0
	v_mov_b32_e32 v14, 0
	v_mov_b32_e32 v15, 0
	v_mov_b32_e32 v16, 0
	v_mov_b32_e32 v17, 0
	v_mov_b32_e32 v18, 0
	v_mov_b32_e32 v19, 0
	v_mov_b32_e32 v20, 0
	v_mov_b32_e32 v21, 0
	v_mov_b32_e32 v22, 0
	v_mov_b32_e32 v23, 0
	v_mov_b32_e32 v24, 0
	v_mov_b32_e32 v25, 0
	v_mov_b32_e32 v26, 0
	v_mov_b32_e32 v27, 0
	v_mov_b32_e32 v28, 0
	v_mov_b32_e32 v29, 0
	v_mov_b32_e32 v30, 0
	v_mov_b32_e32 v31, 0
	v_mov_b32_e32 v32, 0
	v_mov_b32_e32 v33, 0
	v_mov_b32_e32 v34, 0
	v_mov_b32_e32 v35, 0
	v_mov_b32_e32 v36, 0
	v_mov_b32_e32 v37, 0
	v_mov_b32_e32 v38, 0
	v_mov_b32_e32 v39, 0
	v_mov_b32_e32 v40, 0
	v_mov_b32_e32 v41, 0
	v_mov_b32_e32 v42, 0
	v_mov_b32_e32 v43, 0
	v_mov_b32_e32 v44, 0
	v_mov_b32_e32 v45, 0
	v_mov_b32_e32 v46, 0
	v_mov_b32_e32 v47, 0
	v_mov_b32_e32 v48, 0
	v_mov_b32_e32 v49, 0
	v_mov_b32_e32 v50, 0
	v_mov_b32_e32 v51, 0
	v_mov_b32_e32 v52, 0
	v_mov_b32_e32 v53, 0
	v_mov_b32_e32 v54, 0
	v_mov_b32_e32 v55, 0
	v_mov_b32_e32 v56, 0
	v_mov_b32_e32 v57, 0
	v_mov_b32_e32 v58, 0
	v_mov_b32_e32 v59, 0
	v_mov_b32_e32 v60, 0
	v_mov_b32_e32 v61, 0
	v_mov_b32_e32 v62, 0
	v_mov_b32_e32 v63, 0
	v_mov_b32_e32 v64, 0
	v_mov_b32_e32 v65, 0
	v_mov_b32_e32 v165, 0
	v_mov_b32_e32 v163, 0
	s_waitcnt vmcnt(63)
	s_add_i32 s3, s3, s33
	s_cmpk_lt_i32 s3, 0x400
	s_cbranch_scc1 .Lattn_unit
